# RG-LRU scan passes (P7): per unrolled group of 8 steps all address computations and all 24 / 32 loads are issued first instead of load-wait per step
# speedup vs baseline: 1.0114x; 1.0080x over previous
; __device__ __forceinline__ f32x4 unpack4(u32x2 u) { return (f32x4){__uint_as_float(u.x << 16), __uint_as_float(u.x & 0xffff0000u), __uint_as_float(u.y << 16), __uint_as_float(u.y & 0xffff0000u)}; }
; template <int ph>
; __device__ __forceinline__ void run_phase(const Args& args, LAS unsigned char* lds, const int G, const int bx, const bool fin = true) {
;     ...
; #pragma unroll 8
;                 for (int t = 0; t < 32; ++t) { const size_t o = base + (size_t)t * D;
;                     const u32x4 gr = *(const u32x4*)(GR + o), gi = *(const u32x4*)(GI + o), xc = *(const u32x4*)(XC + o);
;                     f32x4 a, bb;
;                     lru_ab(unpack4((u32x2){gr.x, gr.y}), unpack4((u32x2){gi.x, gi.y}), unpack4((u32x2){xc.x, xc.y}), sp0, a, bb); A0 = A0 * a; B0 = a * B0 + bb;
;                     lru_ab(unpack4((u32x2){gr.z, gr.w}), unpack4((u32x2){gi.z, gi.w}), unpack4((u32x2){xc.z, xc.w}), sp1, a, bb); A1 = A1 * a; B1 = a * B1 + bb; }
.LBB0_1061:
	v_lshl_add_u64 v[18:19], v[34:35], 0, s[24:25]
	v_add_co_u32_e32 v176, vcc, s46, v18
	s_nop 1
	v_addc_co_u32_e32 v177, vcc, 0, v19, vcc
	v_add_co_u32_e32 v178, vcc, s52, v18
	s_nop 1
	v_addc_co_u32_e32 v179, vcc, 0, v19, vcc
	v_add_co_u32_e32 v180, vcc, s47, v18
	s_nop 1
	v_addc_co_u32_e32 v181, vcc, 0, v19, vcc
	v_add_co_u32_e32 v182, vcc, s53, v18
	s_nop 1
	v_addc_co_u32_e32 v183, vcc, 0, v19, vcc
	v_add_co_u32_e32 v184, vcc, s48, v18
	s_nop 1
	v_addc_co_u32_e32 v185, vcc, 0, v19, vcc
	v_add_co_u32_e32 v186, vcc, s54, v18
	s_nop 1
	v_addc_co_u32_e32 v187, vcc, 0, v19, vcc
	v_add_co_u32_e32 v188, vcc, s55, v18
	s_nop 1
	v_addc_co_u32_e32 v189, vcc, 0, v19, vcc
	v_add_co_u32_e32 v190, vcc, s62, v18
	s_nop 1
	v_addc_co_u32_e32 v191, vcc, 0, v19, vcc
	v_add_co_u32_e32 v192, vcc, s56, v18
	s_nop 1
	v_addc_co_u32_e32 v193, vcc, 0, v19, vcc
	v_add_co_u32_e32 v194, vcc, s63, v18
	s_nop 1
	v_addc_co_u32_e32 v195, vcc, 0, v19, vcc
	v_add_co_u32_e32 v196, vcc, s57, v18
	s_nop 1
	v_addc_co_u32_e32 v197, vcc, 0, v19, vcc
	v_add_co_u32_e32 v198, vcc, s74, v18
	s_nop 1
	v_addc_co_u32_e32 v199, vcc, 0, v19, vcc
	global_load_dwordx4 v[80:83], v[178:179], off offset:-4096
	global_load_dwordx4 v[84:87], v[182:183], off offset:-4096
	global_load_dwordx4 v[88:91], v[186:187], off offset:-4096
	global_load_dwordx4 v[92:95], v[176:177], off offset:2048
	global_load_dwordx4 v[96:99], v[180:181], off offset:2048
	global_load_dwordx4 v[100:103], v[184:185], off offset:2048
	global_load_dwordx4 v[104:107], v[178:179], off
	global_load_dwordx4 v[108:111], v[182:183], off
	global_load_dwordx4 v[112:115], v[186:187], off
	global_load_dwordx4 v[116:119], v[178:179], off offset:2048
	global_load_dwordx4 v[120:123], v[182:183], off offset:2048
	global_load_dwordx4 v[124:127], v[186:187], off offset:2048
	global_load_dwordx4 v[128:131], v[190:191], off offset:-4096
	global_load_dwordx4 v[132:135], v[194:195], off offset:-4096
	global_load_dwordx4 v[136:139], v[198:199], off offset:-4096
	global_load_dwordx4 v[140:143], v[188:189], off offset:2048
	global_load_dwordx4 v[144:147], v[192:193], off offset:2048
	global_load_dwordx4 v[148:151], v[196:197], off offset:2048
	global_load_dwordx4 v[152:155], v[190:191], off
	global_load_dwordx4 v[156:159], v[194:195], off
	global_load_dwordx4 v[160:163], v[198:199], off
	global_load_dwordx4 v[164:167], v[190:191], off offset:2048
	global_load_dwordx4 v[168:171], v[194:195], off offset:2048
	global_load_dwordx4 v[172:175], v[198:199], off offset:2048
	s_add_u32 s24, s24, 0x4000
	s_nop 0
	s_addc_u32 s25, s25, 0
	s_nop 0
	s_cmp_eq_u32 s24, 0x10000
	s_nop 0
	s_nop 1
	s_nop 0
	s_waitcnt vmcnt(23)
	v_lshlrev_b32_e32 v70, 16, v80
	v_and_b32_e32 v71, 0xffff0000, v80
	v_pk_mul_f32 v[70:71], v[28:29], v[70:71]
	v_lshlrev_b32_e32 v40, 16, v81
	v_mul_f32_e32 v1, 0x3fb8aa3b, v70
	v_exp_f32_e32 v70, v1
	v_mul_f32_e32 v1, 0x3fb8aa3b, v71
	v_exp_f32_e32 v71, v1
	v_and_b32_e32 v41, 0xffff0000, v81
	v_pk_mul_f32 v[40:41], v[26:27], v[40:41]
	v_xor_b32_e32 v78, 0x80000000, v70
	v_mul_f32_e32 v1, 0x3fb8aa3b, v40
	v_xor_b32_e32 v79, 0x80000000, v71
	v_exp_f32_e32 v40, v1
	v_mul_f32_e32 v1, 0x3fb8aa3b, v41
	v_pk_fma_f32 v[78:79], v[78:79], v[70:71], 1.0 op_sel_hi:[1,1,0]
	v_exp_f32_e32 v41, v1
	v_max_f32_e32 v1, 0, v78
	v_xor_b32_e32 v77, 0x80000000, v41
	v_xor_b32_e32 v76, 0x80000000, v40
	v_pk_fma_f32 v[76:77], v[76:77], v[40:41], 1.0 op_sel_hi:[1,1,0]
	s_waitcnt vmcnt(22)
	v_lshlrev_b32_e32 v72, 16, v84
	v_and_b32_e32 v73, 0xffff0000, v84
	v_lshlrev_b32_e32 v44, 16, v85
	v_and_b32_e32 v45, 0xffff0000, v85
	s_waitcnt vmcnt(21)
	v_lshlrev_b32_e32 v74, 16, v88
	v_sqrt_f32_e32 v78, v1
	v_max_f32_e32 v1, 0, v79
	v_and_b32_e32 v75, 0xffff0000, v88
	v_lshlrev_b32_e32 v48, 16, v89
	v_and_b32_e32 v49, 0xffff0000, v89
	v_sqrt_f32_e32 v79, v1
	v_max_f32_e32 v1, 0, v76
	v_pk_mul_f32 v[72:73], v[78:79], v[72:73]
	v_sqrt_f32_e32 v76, v1
	v_max_f32_e32 v1, 0, v77
	v_sqrt_f32_e32 v77, v1
	s_nop 0
	v_pk_mul_f32 v[44:45], v[76:77], v[44:45]
	s_nop 0
	v_pk_mul_f32 v[44:45], v[44:45], v[48:49]
	v_pk_mul_f32 v[48:49], v[72:73], v[74:75]
	v_pk_mul_f32 v[74:75], v[8:9], v[40:41]
	v_pk_fma_f32 v[48:49], v[2:3], v[70:71], v[48:49]
	v_lshlrev_b32_e32 v2, 16, v82
	v_and_b32_e32 v3, 0xffff0000, v82
	v_pk_mul_f32 v[2:3], v[32:33], v[2:3]
	v_pk_fma_f32 v[40:41], v[4:5], v[40:41], v[44:45]
	v_mul_f32_e32 v1, 0x3fb8aa3b, v2
	v_exp_f32_e32 v2, v1
	v_mul_f32_e32 v1, 0x3fb8aa3b, v3
	v_exp_f32_e32 v3, v1
	v_lshlrev_b32_e32 v4, 16, v83
	v_and_b32_e32 v5, 0xffff0000, v83
	v_pk_mul_f32 v[4:5], v[30:31], v[4:5]
	v_lshlrev_b32_e32 v42, 16, v90
	v_and_b32_e32 v43, 0xffff0000, v90
	v_lshlrev_b32_e32 v44, 16, v91
	v_and_b32_e32 v45, 0xffff0000, v91
	v_mul_f32_e32 v1, 0x3fb8aa3b, v4
	v_xor_b32_e32 v51, 0x80000000, v3
	v_xor_b32_e32 v50, 0x80000000, v2
	v_exp_f32_e32 v4, v1
	v_mul_f32_e32 v1, 0x3fb8aa3b, v5
	v_pk_fma_f32 v[50:51], v[50:51], v[2:3], 1.0 op_sel_hi:[1,1,0]
	v_exp_f32_e32 v5, v1
	v_max_f32_e32 v1, 0, v50
	v_pk_mul_f32 v[72:73], v[6:7], v[70:71]
	v_lshlrev_b32_e32 v6, 16, v86
	v_and_b32_e32 v7, 0xffff0000, v86
	v_lshlrev_b32_e32 v8, 16, v87
	v_and_b32_e32 v9, 0xffff0000, v87
	v_xor_b32_e32 v47, 0x80000000, v5
	v_xor_b32_e32 v46, 0x80000000, v4
	v_pk_fma_f32 v[46:47], v[46:47], v[4:5], 1.0 op_sel_hi:[1,1,0]
	s_nop 0
	v_sqrt_f32_e32 v50, v1
	v_max_f32_e32 v1, 0, v51
	v_sqrt_f32_e32 v51, v1
	v_max_f32_e32 v1, 0, v46
	v_pk_mul_f32 v[6:7], v[50:51], v[6:7]
	v_pk_mul_f32 v[6:7], v[6:7], v[42:43]
	v_pk_mul_f32 v[42:43], v[10:11], v[2:3]
	v_pk_fma_f32 v[14:15], v[14:15], v[2:3], v[6:7]
	v_sqrt_f32_e32 v46, v1
	v_max_f32_e32 v1, 0, v47
	v_sqrt_f32_e32 v47, v1
	s_nop 0
	v_pk_mul_f32 v[8:9], v[46:47], v[8:9]
	s_nop 0
	v_pk_mul_f32 v[8:9], v[8:9], v[44:45]
	v_pk_mul_f32 v[44:45], v[12:13], v[4:5]
	v_pk_fma_f32 v[16:17], v[16:17], v[4:5], v[8:9]
	s_waitcnt vmcnt(20)
; __device__ __forceinline__ f32x4 unpack4(u32x2 u) { return (f32x4){__uint_as_float(u.x << 16), __uint_as_float(u.x & 0xffff0000u), __uint_as_float(u.y << 16), __uint_as_float(u.y & 0xffff0000u)}; }
; template <int ph>
; __device__ __forceinline__ void run_phase(const Args& args, LAS unsigned char* lds, const int G, const int bx, const bool fin = true) {
;     ...
; #pragma unroll 8
;                 for (int t = 0; t < 32; ++t) { const size_t o = base + (size_t)t * D;
;                     const u32x4 gr = *(const u32x4*)(GR + o), gi = *(const u32x4*)(GI + o), xc = *(const u32x4*)(XC + o);
;                     f32x4 a, bb;
;                     lru_ab(unpack4((u32x2){gr.x, gr.y}), unpack4((u32x2){gi.x, gi.y}), unpack4((u32x2){xc.x, xc.y}), sp0, a, bb); A0 = A0 * a; B0 = a * B0 + bb;
;                     lru_ab(unpack4((u32x2){gr.z, gr.w}), unpack4((u32x2){gi.z, gi.w}), unpack4((u32x2){xc.z, xc.w}), sp1, a, bb); A1 = A1 * a; B1 = a * B1 + bb; }
	v_lshlrev_b32_e32 v46, 16, v92
	v_and_b32_e32 v47, 0xffff0000, v92
	v_pk_mul_f32 v[46:47], v[28:29], v[46:47]
	v_lshlrev_b32_e32 v2, 16, v93
	v_mul_f32_e32 v1, 0x3fb8aa3b, v46
	v_exp_f32_e32 v46, v1
	v_mul_f32_e32 v1, 0x3fb8aa3b, v47
	v_exp_f32_e32 v47, v1
	v_and_b32_e32 v3, 0xffff0000, v93
	v_pk_mul_f32 v[2:3], v[26:27], v[2:3]
	v_xor_b32_e32 v66, 0x80000000, v46
	v_mul_f32_e32 v1, 0x3fb8aa3b, v2
	v_xor_b32_e32 v67, 0x80000000, v47
	v_exp_f32_e32 v2, v1
	v_mul_f32_e32 v1, 0x3fb8aa3b, v3
	v_pk_fma_f32 v[66:67], v[66:67], v[46:47], 1.0 op_sel_hi:[1,1,0]
	v_exp_f32_e32 v3, v1
	v_max_f32_e32 v1, 0, v66
	v_xor_b32_e32 v65, 0x80000000, v3
	v_xor_b32_e32 v64, 0x80000000, v2
	v_pk_fma_f32 v[64:65], v[64:65], v[2:3], 1.0 op_sel_hi:[1,1,0]
	s_waitcnt vmcnt(19)
	v_lshlrev_b32_e32 v50, 16, v96
	v_and_b32_e32 v51, 0xffff0000, v96
	v_lshlrev_b32_e32 v6, 16, v97
	v_and_b32_e32 v7, 0xffff0000, v97
	s_waitcnt vmcnt(18)
	v_lshlrev_b32_e32 v62, 16, v100
	v_and_b32_e32 v63, 0xffff0000, v100
	v_sqrt_f32_e32 v66, v1
	v_max_f32_e32 v1, 0, v67
	v_lshlrev_b32_e32 v10, 16, v101
	v_and_b32_e32 v11, 0xffff0000, v101
	v_sqrt_f32_e32 v67, v1
	v_max_f32_e32 v1, 0, v64
	v_pk_mul_f32 v[50:51], v[66:67], v[50:51]
	v_pk_mul_f32 v[50:51], v[50:51], v[62:63]
	v_pk_mul_f32 v[62:63], v[74:75], v[2:3]
	v_sqrt_f32_e32 v64, v1
	v_max_f32_e32 v1, 0, v65
	v_sqrt_f32_e32 v65, v1
	s_nop 0
	v_pk_mul_f32 v[6:7], v[64:65], v[6:7]
	v_pk_mul_f32 v[64:65], v[72:73], v[46:47]
	v_pk_mul_f32 v[6:7], v[6:7], v[10:11]
	v_pk_fma_f32 v[46:47], v[48:49], v[46:47], v[50:51]
	v_pk_fma_f32 v[40:41], v[40:41], v[2:3], v[6:7]
	v_lshlrev_b32_e32 v2, 16, v94
	v_and_b32_e32 v3, 0xffff0000, v94
	v_pk_mul_f32 v[2:3], v[32:33], v[2:3]
	v_lshlrev_b32_e32 v4, 16, v95
	v_mul_f32_e32 v1, 0x3fb8aa3b, v2
	v_exp_f32_e32 v2, v1
	v_mul_f32_e32 v1, 0x3fb8aa3b, v3
	v_exp_f32_e32 v3, v1
	v_and_b32_e32 v5, 0xffff0000, v95
	v_pk_mul_f32 v[4:5], v[30:31], v[4:5]
	v_xor_b32_e32 v50, 0x80000000, v2
	v_mul_f32_e32 v1, 0x3fb8aa3b, v4
	v_xor_b32_e32 v51, 0x80000000, v3
	v_exp_f32_e32 v4, v1
	v_mul_f32_e32 v1, 0x3fb8aa3b, v5
	v_pk_fma_f32 v[50:51], v[50:51], v[2:3], 1.0 op_sel_hi:[1,1,0]
	v_exp_f32_e32 v5, v1
	v_max_f32_e32 v1, 0, v50
	v_xor_b32_e32 v49, 0x80000000, v5
	v_xor_b32_e32 v48, 0x80000000, v4
	v_pk_fma_f32 v[48:49], v[48:49], v[4:5], 1.0 op_sel_hi:[1,1,0]
	v_lshlrev_b32_e32 v6, 16, v98
	v_and_b32_e32 v7, 0xffff0000, v98
	v_lshlrev_b32_e32 v8, 16, v99
	v_and_b32_e32 v9, 0xffff0000, v99
	v_lshlrev_b32_e32 v10, 16, v102
	v_and_b32_e32 v11, 0xffff0000, v102
	v_sqrt_f32_e32 v50, v1
	v_max_f32_e32 v1, 0, v51
	v_lshlrev_b32_e32 v12, 16, v103
	v_and_b32_e32 v13, 0xffff0000, v103
	v_pk_mul_f32 v[44:45], v[44:45], v[4:5]
	v_pk_mul_f32 v[42:43], v[42:43], v[2:3]
	v_sqrt_f32_e32 v51, v1
	v_max_f32_e32 v1, 0, v48
	v_pk_mul_f32 v[6:7], v[50:51], v[6:7]
	v_pk_mul_f32 v[6:7], v[6:7], v[10:11]
	v_pk_fma_f32 v[14:15], v[14:15], v[2:3], v[6:7]
	v_sqrt_f32_e32 v48, v1
	v_max_f32_e32 v1, 0, v49
	v_sqrt_f32_e32 v49, v1
	s_nop 0
	v_pk_mul_f32 v[8:9], v[48:49], v[8:9]
	s_nop 0
	v_pk_mul_f32 v[8:9], v[8:9], v[12:13]
	s_nop 0
	v_pk_fma_f32 v[16:17], v[16:17], v[4:5], v[8:9]
	s_waitcnt vmcnt(17)
	v_lshlrev_b32_e32 v48, 16, v104
	v_and_b32_e32 v49, 0xffff0000, v104
	v_pk_mul_f32 v[48:49], v[28:29], v[48:49]
	v_lshlrev_b32_e32 v2, 16, v105
	v_mul_f32_e32 v1, 0x3fb8aa3b, v48
	v_exp_f32_e32 v48, v1
	v_mul_f32_e32 v1, 0x3fb8aa3b, v49
	v_exp_f32_e32 v49, v1
	v_and_b32_e32 v3, 0xffff0000, v105
	v_pk_mul_f32 v[2:3], v[26:27], v[2:3]
	v_xor_b32_e32 v72, 0x80000000, v48
	v_mul_f32_e32 v1, 0x3fb8aa3b, v2
	v_xor_b32_e32 v73, 0x80000000, v49
	v_exp_f32_e32 v2, v1
	v_mul_f32_e32 v1, 0x3fb8aa3b, v3
	v_pk_fma_f32 v[72:73], v[72:73], v[48:49], 1.0 op_sel_hi:[1,1,0]
	v_exp_f32_e32 v3, v1
	v_max_f32_e32 v1, 0, v72
	v_xor_b32_e32 v71, 0x80000000, v3
	v_xor_b32_e32 v70, 0x80000000, v2
	v_pk_fma_f32 v[70:71], v[70:71], v[2:3], 1.0 op_sel_hi:[1,1,0]
	s_waitcnt vmcnt(16)
	v_lshlrev_b32_e32 v50, 16, v108
	v_and_b32_e32 v51, 0xffff0000, v108
	v_lshlrev_b32_e32 v6, 16, v109
	v_and_b32_e32 v7, 0xffff0000, v109
	s_waitcnt vmcnt(15)
	v_lshlrev_b32_e32 v66, 16, v112
	v_and_b32_e32 v67, 0xffff0000, v112
	v_sqrt_f32_e32 v72, v1
	v_max_f32_e32 v1, 0, v73
	v_lshlrev_b32_e32 v10, 16, v113
	v_and_b32_e32 v11, 0xffff0000, v113
	v_pk_mul_f32 v[62:63], v[62:63], v[2:3]
	v_sqrt_f32_e32 v73, v1
	v_max_f32_e32 v1, 0, v70
	v_pk_mul_f32 v[50:51], v[72:73], v[50:51]
	v_sqrt_f32_e32 v70, v1
	v_max_f32_e32 v1, 0, v71
	v_sqrt_f32_e32 v71, v1
	s_nop 0
	v_pk_mul_f32 v[6:7], v[70:71], v[6:7]
	s_nop 0
	v_pk_mul_f32 v[6:7], v[6:7], v[10:11]
	v_pk_mul_f32 v[10:11], v[50:51], v[66:67]
	v_pk_fma_f32 v[40:41], v[40:41], v[2:3], v[6:7]
	v_lshlrev_b32_e32 v2, 16, v106
	v_and_b32_e32 v3, 0xffff0000, v106
	v_pk_mul_f32 v[2:3], v[32:33], v[2:3]
	v_lshlrev_b32_e32 v4, 16, v107
	v_mul_f32_e32 v1, 0x3fb8aa3b, v2
	v_exp_f32_e32 v2, v1
	v_mul_f32_e32 v1, 0x3fb8aa3b, v3
	v_exp_f32_e32 v3, v1
	v_and_b32_e32 v5, 0xffff0000, v107
	v_pk_mul_f32 v[4:5], v[30:31], v[4:5]
	v_pk_mul_f32 v[50:51], v[64:65], v[48:49]
	v_mul_f32_e32 v1, 0x3fb8aa3b, v4
	v_xor_b32_e32 v65, 0x80000000, v3
	v_xor_b32_e32 v64, 0x80000000, v2
	v_exp_f32_e32 v4, v1
	v_mul_f32_e32 v1, 0x3fb8aa3b, v5
	v_pk_fma_f32 v[64:65], v[64:65], v[2:3], 1.0 op_sel_hi:[1,1,0]
	v_exp_f32_e32 v5, v1
	v_max_f32_e32 v1, 0, v64
	v_pk_fma_f32 v[46:47], v[46:47], v[48:49], v[10:11]
	v_xor_b32_e32 v49, 0x80000000, v5
	v_xor_b32_e32 v48, 0x80000000, v4
	v_pk_fma_f32 v[48:49], v[48:49], v[4:5], 1.0 op_sel_hi:[1,1,0]
	v_lshlrev_b32_e32 v6, 16, v110
	v_and_b32_e32 v7, 0xffff0000, v110
	v_lshlrev_b32_e32 v8, 16, v111
	v_and_b32_e32 v9, 0xffff0000, v111
	v_lshlrev_b32_e32 v10, 16, v114
	v_sqrt_f32_e32 v64, v1
	v_max_f32_e32 v1, 0, v65
	v_and_b32_e32 v11, 0xffff0000, v114
	v_lshlrev_b32_e32 v12, 16, v115
	v_and_b32_e32 v13, 0xffff0000, v115
	v_pk_mul_f32 v[44:45], v[44:45], v[4:5]
	v_pk_mul_f32 v[42:43], v[42:43], v[2:3]
	v_sqrt_f32_e32 v65, v1
	v_max_f32_e32 v1, 0, v48
	v_pk_mul_f32 v[6:7], v[64:65], v[6:7]
	v_pk_mul_f32 v[6:7], v[6:7], v[10:11]
	v_sqrt_f32_e32 v48, v1
	v_max_f32_e32 v1, 0, v49
	v_sqrt_f32_e32 v49, v1
	s_nop 0
	v_pk_mul_f32 v[8:9], v[48:49], v[8:9]
	v_pk_fma_f32 v[48:49], v[14:15], v[2:3], v[6:7]
	v_pk_mul_f32 v[8:9], v[8:9], v[12:13]
	s_nop 0
	v_pk_fma_f32 v[8:9], v[16:17], v[4:5], v[8:9]
	s_nop 0
	s_waitcnt vmcnt(14)
; __device__ __forceinline__ f32x4 unpack4(u32x2 u) { return (f32x4){__uint_as_float(u.x << 16), __uint_as_float(u.x & 0xffff0000u), __uint_as_float(u.y << 16), __uint_as_float(u.y & 0xffff0000u)}; }
; template <int ph>
; __device__ __forceinline__ void run_phase(const Args& args, LAS unsigned char* lds, const int G, const int bx, const bool fin = true) {
;     ...
; #pragma unroll 8
;                 for (int t = 0; t < 32; ++t) { const size_t o = base + (size_t)t * D;
;                     const u32x4 gr = *(const u32x4*)(GR + o), gi = *(const u32x4*)(GI + o), xc = *(const u32x4*)(XC + o);
;                     f32x4 a, bb;
;                     lru_ab(unpack4((u32x2){gr.x, gr.y}), unpack4((u32x2){gi.x, gi.y}), unpack4((u32x2){xc.x, xc.y}), sp0, a, bb); A0 = A0 * a; B0 = a * B0 + bb;
;                     lru_ab(unpack4((u32x2){gr.z, gr.w}), unpack4((u32x2){gi.z, gi.w}), unpack4((u32x2){xc.z, xc.w}), sp1, a, bb); A1 = A1 * a; B1 = a * B1 + bb; }
	v_lshlrev_b32_e32 v2, 16, v116
	v_and_b32_e32 v3, 0xffff0000, v116
	v_pk_mul_f32 v[2:3], v[28:29], v[2:3]
	s_waitcnt vmcnt(12)
	v_lshlrev_b32_e32 v16, 16, v124
	v_mul_f32_e32 v1, 0x3fb8aa3b, v2
	v_and_b32_e32 v17, 0xffff0000, v124
	v_exp_f32_e32 v36, v1
	v_mul_f32_e32 v1, 0x3fb8aa3b, v3
	v_lshlrev_b32_e32 v20, 16, v125
	v_and_b32_e32 v21, 0xffff0000, v125
	v_exp_f32_e32 v37, v1
	v_lshlrev_b32_e32 v4, 16, v117
	v_and_b32_e32 v5, 0xffff0000, v117
	v_pk_mul_f32 v[4:5], v[26:27], v[4:5]
	v_xor_b32_e32 v65, 0x80000000, v37
	v_mul_f32_e32 v1, 0x3fb8aa3b, v4
	v_xor_b32_e32 v64, 0x80000000, v36
	v_exp_f32_e32 v4, v1
	v_mul_f32_e32 v1, 0x3fb8aa3b, v5
	v_pk_fma_f32 v[64:65], v[64:65], v[36:37], 1.0 op_sel_hi:[1,1,0]
	v_exp_f32_e32 v5, v1
	v_max_f32_e32 v1, 0, v64
	v_xor_b32_e32 v3, 0x80000000, v5
	v_xor_b32_e32 v2, 0x80000000, v4
	v_pk_fma_f32 v[2:3], v[2:3], v[4:5], 1.0 op_sel_hi:[1,1,0]
	v_lshlrev_b32_e32 v10, 16, v120
	v_and_b32_e32 v11, 0xffff0000, v120
	v_lshlrev_b32_e32 v12, 16, v121
	v_and_b32_e32 v13, 0xffff0000, v121
	v_sqrt_f32_e32 v64, v1
	v_max_f32_e32 v1, 0, v65
	v_sqrt_f32_e32 v65, v1
	v_max_f32_e32 v1, 0, v2
	v_pk_mul_f32 v[10:11], v[64:65], v[10:11]
	v_sqrt_f32_e32 v2, v1
	v_max_f32_e32 v1, 0, v3
	v_sqrt_f32_e32 v3, v1
	s_nop 0
	v_pk_mul_f32 v[2:3], v[2:3], v[12:13]
	v_pk_mul_f32 v[12:13], v[10:11], v[16:17]
	v_pk_mul_f32 v[16:17], v[2:3], v[20:21]
	v_pk_mul_f32 v[2:3], v[62:63], v[4:5]
	v_pk_fma_f32 v[4:5], v[40:41], v[4:5], v[16:17]
	v_lshlrev_b32_e32 v16, 16, v118
	v_and_b32_e32 v17, 0xffff0000, v118
	v_pk_mul_f32 v[16:17], v[32:33], v[16:17]
	v_lshlrev_b32_e32 v6, 16, v119
	v_mul_f32_e32 v1, 0x3fb8aa3b, v16
	v_exp_f32_e32 v16, v1
	v_mul_f32_e32 v1, 0x3fb8aa3b, v17
	v_exp_f32_e32 v17, v1
	v_and_b32_e32 v7, 0xffff0000, v119
	v_pk_mul_f32 v[6:7], v[30:31], v[6:7]
	v_pk_fma_f32 v[12:13], v[46:47], v[36:37], v[12:13]
	v_mul_f32_e32 v1, 0x3fb8aa3b, v6
	v_xor_b32_e32 v47, 0x80000000, v17
	v_xor_b32_e32 v46, 0x80000000, v16
	v_exp_f32_e32 v40, v1
	v_mul_f32_e32 v1, 0x3fb8aa3b, v7
	v_pk_fma_f32 v[46:47], v[46:47], v[16:17], 1.0 op_sel_hi:[1,1,0]
	v_exp_f32_e32 v41, v1
	v_max_f32_e32 v1, 0, v46
	v_pk_mul_f32 v[10:11], v[50:51], v[36:37]
	v_xor_b32_e32 v7, 0x80000000, v41
	v_xor_b32_e32 v6, 0x80000000, v40
	v_pk_fma_f32 v[6:7], v[6:7], v[40:41], 1.0 op_sel_hi:[1,1,0]
	v_lshlrev_b32_e32 v20, 16, v122
	v_and_b32_e32 v21, 0xffff0000, v122
	v_lshlrev_b32_e32 v14, 16, v123
	v_and_b32_e32 v15, 0xffff0000, v123
	v_lshlrev_b32_e32 v36, 16, v126
	v_sqrt_f32_e32 v46, v1
	v_max_f32_e32 v1, 0, v47
	v_and_b32_e32 v37, 0xffff0000, v126
	v_lshlrev_b32_e32 v38, 16, v127
	v_and_b32_e32 v39, 0xffff0000, v127
	v_sqrt_f32_e32 v47, v1
	v_max_f32_e32 v1, 0, v6
	v_sqrt_f32_e32 v6, v1
	v_max_f32_e32 v1, 0, v7
	v_sqrt_f32_e32 v7, v1
	s_nop 0
	v_pk_mul_f32 v[6:7], v[6:7], v[14:15]
	v_pk_mul_f32 v[14:15], v[46:47], v[20:21]
	s_nop 0
	v_pk_mul_f32 v[20:21], v[14:15], v[36:37]
	v_pk_mul_f32 v[14:15], v[42:43], v[16:17]
	v_pk_fma_f32 v[16:17], v[48:49], v[16:17], v[20:21]
	v_pk_mul_f32 v[36:37], v[6:7], v[38:39]
	s_nop 0
	v_pk_fma_f32 v[8:9], v[8:9], v[40:41], v[36:37]
	s_nop 0
	v_pk_mul_f32 v[6:7], v[44:45], v[40:41]
	s_nop 0
	s_nop 1
	s_nop 0
	s_waitcnt vmcnt(11)
	v_lshlrev_b32_e32 v18, 16, v128
	v_and_b32_e32 v19, 0xffff0000, v128
	v_pk_mul_f32 v[18:19], v[28:29], v[18:19]
	v_lshlrev_b32_e32 v40, 16, v129
	v_mul_f32_e32 v1, 0x3fb8aa3b, v18
	v_exp_f32_e32 v74, v1
	v_mul_f32_e32 v1, 0x3fb8aa3b, v19
	v_exp_f32_e32 v75, v1
	v_and_b32_e32 v41, 0xffff0000, v129
	v_pk_mul_f32 v[40:41], v[26:27], v[40:41]
	v_xor_b32_e32 v76, 0x80000000, v74
	v_mul_f32_e32 v1, 0x3fb8aa3b, v40
	v_xor_b32_e32 v77, 0x80000000, v75
	v_exp_f32_e32 v40, v1
	v_mul_f32_e32 v1, 0x3fb8aa3b, v41
	v_pk_fma_f32 v[76:77], v[76:77], v[74:75], 1.0 op_sel_hi:[1,1,0]
	v_exp_f32_e32 v41, v1
	v_max_f32_e32 v1, 0, v76
	v_xor_b32_e32 v19, 0x80000000, v41
	v_xor_b32_e32 v18, 0x80000000, v40
	v_pk_fma_f32 v[18:19], v[18:19], v[40:41], 1.0 op_sel_hi:[1,1,0]
	s_waitcnt vmcnt(10)
	v_lshlrev_b32_e32 v48, 16, v132
	v_and_b32_e32 v49, 0xffff0000, v132
	v_lshlrev_b32_e32 v62, 16, v133
	v_and_b32_e32 v63, 0xffff0000, v133
	v_pk_mul_f32 v[10:11], v[10:11], v[74:75]
	s_waitcnt vmcnt(9)
	v_lshlrev_b32_e32 v66, 16, v136
	v_sqrt_f32_e32 v76, v1
	v_max_f32_e32 v1, 0, v77
	v_and_b32_e32 v67, 0xffff0000, v136
	v_lshlrev_b32_e32 v70, 16, v137
	v_and_b32_e32 v71, 0xffff0000, v137
	v_sqrt_f32_e32 v77, v1
	v_max_f32_e32 v1, 0, v18
	v_pk_mul_f32 v[48:49], v[76:77], v[48:49]
	v_pk_mul_f32 v[48:49], v[48:49], v[66:67]
	v_sqrt_f32_e32 v18, v1
	v_max_f32_e32 v1, 0, v19
	v_sqrt_f32_e32 v19, v1
	s_nop 0
	v_pk_mul_f32 v[18:19], v[18:19], v[62:63]
	s_nop 0
	v_pk_mul_f32 v[62:63], v[18:19], v[70:71]
	v_pk_mul_f32 v[18:19], v[2:3], v[40:41]
	v_pk_fma_f32 v[2:3], v[12:13], v[74:75], v[48:49]
	v_pk_fma_f32 v[12:13], v[4:5], v[40:41], v[62:63]
	v_lshlrev_b32_e32 v4, 16, v130
	v_and_b32_e32 v5, 0xffff0000, v130
	v_pk_mul_f32 v[4:5], v[32:33], v[4:5]
	v_lshlrev_b32_e32 v40, 16, v131
	v_mul_f32_e32 v1, 0x3fb8aa3b, v4
	v_exp_f32_e32 v66, v1
	v_mul_f32_e32 v1, 0x3fb8aa3b, v5
	v_exp_f32_e32 v67, v1
	v_and_b32_e32 v41, 0xffff0000, v131
	v_pk_mul_f32 v[40:41], v[30:31], v[40:41]
	v_xor_b32_e32 v70, 0x80000000, v66
	v_mul_f32_e32 v1, 0x3fb8aa3b, v40
	v_xor_b32_e32 v71, 0x80000000, v67
	v_exp_f32_e32 v40, v1
	v_mul_f32_e32 v1, 0x3fb8aa3b, v41
	v_pk_fma_f32 v[70:71], v[70:71], v[66:67], 1.0 op_sel_hi:[1,1,0]
	v_exp_f32_e32 v41, v1
	v_max_f32_e32 v1, 0, v70
	v_xor_b32_e32 v5, 0x80000000, v41
	v_xor_b32_e32 v4, 0x80000000, v40
	v_pk_fma_f32 v[4:5], v[4:5], v[40:41], 1.0 op_sel_hi:[1,1,0]
	v_lshlrev_b32_e32 v48, 16, v134
	v_and_b32_e32 v49, 0xffff0000, v134
	v_lshlrev_b32_e32 v50, 16, v135
	v_and_b32_e32 v51, 0xffff0000, v135
	v_lshlrev_b32_e32 v62, 16, v138
	v_and_b32_e32 v63, 0xffff0000, v138
	v_sqrt_f32_e32 v70, v1
	v_max_f32_e32 v1, 0, v71
	v_lshlrev_b32_e32 v64, 16, v139
	v_and_b32_e32 v65, 0xffff0000, v139
	v_sqrt_f32_e32 v71, v1
	v_max_f32_e32 v1, 0, v4
	v_pk_mul_f32 v[48:49], v[70:71], v[48:49]
	v_pk_mul_f32 v[48:49], v[48:49], v[62:63]
	v_sqrt_f32_e32 v4, v1
	v_max_f32_e32 v1, 0, v5
	v_sqrt_f32_e32 v5, v1
	s_nop 0
	v_pk_mul_f32 v[4:5], v[4:5], v[50:51]
	s_nop 0
	v_pk_mul_f32 v[50:51], v[4:5], v[64:65]
	v_pk_mul_f32 v[4:5], v[14:15], v[66:67]
	v_pk_mul_f32 v[14:15], v[6:7], v[40:41]
	v_pk_fma_f32 v[6:7], v[16:17], v[66:67], v[48:49]
	v_pk_fma_f32 v[8:9], v[8:9], v[40:41], v[50:51]
	s_nop 0
	s_waitcnt vmcnt(8)
; __device__ __forceinline__ f32x4 unpack4(u32x2 u) { return (f32x4){__uint_as_float(u.x << 16), __uint_as_float(u.x & 0xffff0000u), __uint_as_float(u.y << 16), __uint_as_float(u.y & 0xffff0000u)}; }
; template <int ph>
; __device__ __forceinline__ void run_phase(const Args& args, LAS unsigned char* lds, const int G, const int bx, const bool fin = true) {
;     ...
; #pragma unroll 8
;                 for (int t = 0; t < 32; ++t) { const size_t o = base + (size_t)t * D;
;                     const u32x4 gr = *(const u32x4*)(GR + o), gi = *(const u32x4*)(GI + o), xc = *(const u32x4*)(XC + o);
;                     f32x4 a, bb;
;                     lru_ab(unpack4((u32x2){gr.x, gr.y}), unpack4((u32x2){gi.x, gi.y}), unpack4((u32x2){xc.x, xc.y}), sp0, a, bb); A0 = A0 * a; B0 = a * B0 + bb;
;                     lru_ab(unpack4((u32x2){gr.z, gr.w}), unpack4((u32x2){gi.z, gi.w}), unpack4((u32x2){xc.z, xc.w}), sp1, a, bb); A1 = A1 * a; B1 = a * B1 + bb; }
	v_lshlrev_b32_e32 v16, 16, v140
	v_and_b32_e32 v17, 0xffff0000, v140
	v_pk_mul_f32 v[16:17], v[28:29], v[16:17]
	v_lshlrev_b32_e32 v20, 16, v141
	v_mul_f32_e32 v1, 0x3fb8aa3b, v16
	v_exp_f32_e32 v66, v1
	v_mul_f32_e32 v1, 0x3fb8aa3b, v17
	v_exp_f32_e32 v67, v1
	v_and_b32_e32 v21, 0xffff0000, v141
	v_pk_mul_f32 v[20:21], v[26:27], v[20:21]
	v_xor_b32_e32 v70, 0x80000000, v66
	v_mul_f32_e32 v1, 0x3fb8aa3b, v20
	v_xor_b32_e32 v71, 0x80000000, v67
	v_exp_f32_e32 v20, v1
	v_mul_f32_e32 v1, 0x3fb8aa3b, v21
	v_pk_fma_f32 v[70:71], v[70:71], v[66:67], 1.0 op_sel_hi:[1,1,0]
	v_exp_f32_e32 v21, v1
	v_max_f32_e32 v1, 0, v70
	v_xor_b32_e32 v17, 0x80000000, v21
	v_xor_b32_e32 v16, 0x80000000, v20
	v_pk_fma_f32 v[16:17], v[16:17], v[20:21], 1.0 op_sel_hi:[1,1,0]
	s_waitcnt vmcnt(7)
	v_lshlrev_b32_e32 v40, 16, v144
	v_and_b32_e32 v41, 0xffff0000, v144
	v_lshlrev_b32_e32 v48, 16, v145
	v_and_b32_e32 v49, 0xffff0000, v145
	s_waitcnt vmcnt(6)
	v_lshlrev_b32_e32 v62, 16, v148
	v_and_b32_e32 v63, 0xffff0000, v148
	v_sqrt_f32_e32 v70, v1
	v_max_f32_e32 v1, 0, v71
	v_lshlrev_b32_e32 v36, 16, v149
	v_and_b32_e32 v37, 0xffff0000, v149
	v_sqrt_f32_e32 v71, v1
	v_max_f32_e32 v1, 0, v16
	v_pk_mul_f32 v[40:41], v[70:71], v[40:41]
	v_pk_mul_f32 v[40:41], v[40:41], v[62:63]
	v_sqrt_f32_e32 v16, v1
	v_max_f32_e32 v1, 0, v17
	v_sqrt_f32_e32 v17, v1
	s_nop 0
	v_pk_mul_f32 v[16:17], v[16:17], v[48:49]
	v_lshlrev_b32_e32 v48, 16, v150
	v_pk_mul_f32 v[36:37], v[16:17], v[36:37]
	v_pk_mul_f32 v[16:17], v[18:19], v[20:21]
	v_pk_mul_f32 v[18:19], v[10:11], v[66:67]
	v_pk_fma_f32 v[10:11], v[12:13], v[20:21], v[36:37]
	v_pk_fma_f32 v[20:21], v[2:3], v[66:67], v[40:41]
	v_lshlrev_b32_e32 v2, 16, v142
	v_and_b32_e32 v3, 0xffff0000, v142
	v_pk_mul_f32 v[2:3], v[32:33], v[2:3]
	v_lshlrev_b32_e32 v12, 16, v143
	v_mul_f32_e32 v1, 0x3fb8aa3b, v2
	v_exp_f32_e32 v2, v1
	v_mul_f32_e32 v1, 0x3fb8aa3b, v3
	v_exp_f32_e32 v3, v1
	v_and_b32_e32 v13, 0xffff0000, v143
	v_pk_mul_f32 v[12:13], v[30:31], v[12:13]
	v_xor_b32_e32 v62, 0x80000000, v2
	v_mul_f32_e32 v1, 0x3fb8aa3b, v12
	v_xor_b32_e32 v63, 0x80000000, v3
	v_exp_f32_e32 v50, v1
	v_mul_f32_e32 v1, 0x3fb8aa3b, v13
	v_pk_fma_f32 v[62:63], v[62:63], v[2:3], 1.0 op_sel_hi:[1,1,0]
	v_exp_f32_e32 v51, v1
	v_max_f32_e32 v1, 0, v62
	v_xor_b32_e32 v13, 0x80000000, v51
	v_xor_b32_e32 v12, 0x80000000, v50
	v_pk_fma_f32 v[12:13], v[12:13], v[50:51], 1.0 op_sel_hi:[1,1,0]
	v_lshlrev_b32_e32 v36, 16, v146
	v_and_b32_e32 v37, 0xffff0000, v146
	v_lshlrev_b32_e32 v40, 16, v147
	v_and_b32_e32 v41, 0xffff0000, v147
	v_and_b32_e32 v49, 0xffff0000, v150
	v_lshlrev_b32_e32 v38, 16, v151
	v_sqrt_f32_e32 v62, v1
	v_max_f32_e32 v1, 0, v63
	v_and_b32_e32 v39, 0xffff0000, v151
	v_sqrt_f32_e32 v63, v1
	v_max_f32_e32 v1, 0, v12
	v_pk_mul_f32 v[36:37], v[62:63], v[36:37]
	v_pk_mul_f32 v[36:37], v[36:37], v[48:49]
	v_pk_fma_f32 v[36:37], v[6:7], v[2:3], v[36:37]
	v_sqrt_f32_e32 v12, v1
	v_max_f32_e32 v1, 0, v13
	v_sqrt_f32_e32 v13, v1
	s_nop 0
	v_pk_mul_f32 v[12:13], v[12:13], v[40:41]
	s_nop 0
	v_pk_mul_f32 v[38:39], v[12:13], v[38:39]
	v_pk_mul_f32 v[12:13], v[14:15], v[50:51]
	v_pk_mul_f32 v[14:15], v[4:5], v[2:3]
	v_pk_fma_f32 v[8:9], v[8:9], v[50:51], v[38:39]
	s_waitcnt vmcnt(5)
	v_lshlrev_b32_e32 v6, 16, v152
	v_and_b32_e32 v7, 0xffff0000, v152
	v_pk_mul_f32 v[6:7], v[28:29], v[6:7]
	v_lshlrev_b32_e32 v2, 16, v153
	v_mul_f32_e32 v1, 0x3fb8aa3b, v6
	v_exp_f32_e32 v66, v1
	v_mul_f32_e32 v1, 0x3fb8aa3b, v7
	v_exp_f32_e32 v67, v1
	v_and_b32_e32 v3, 0xffff0000, v153
	v_pk_mul_f32 v[2:3], v[26:27], v[2:3]
	v_xor_b32_e32 v6, 0x80000000, v66
	v_mul_f32_e32 v1, 0x3fb8aa3b, v2
	v_xor_b32_e32 v7, 0x80000000, v67
	v_exp_f32_e32 v70, v1
	v_mul_f32_e32 v1, 0x3fb8aa3b, v3
	v_pk_fma_f32 v[6:7], v[6:7], v[66:67], 1.0 op_sel_hi:[1,1,0]
	v_exp_f32_e32 v71, v1
	v_max_f32_e32 v1, 0, v6
	v_xor_b32_e32 v3, 0x80000000, v71
	v_xor_b32_e32 v2, 0x80000000, v70
	v_pk_fma_f32 v[2:3], v[2:3], v[70:71], 1.0 op_sel_hi:[1,1,0]
	s_waitcnt vmcnt(4)
	v_lshlrev_b32_e32 v48, 16, v156
	v_and_b32_e32 v49, 0xffff0000, v156
	v_lshlrev_b32_e32 v38, 16, v157
	v_and_b32_e32 v39, 0xffff0000, v157
	s_waitcnt vmcnt(3)
	v_lshlrev_b32_e32 v50, 16, v160
	v_and_b32_e32 v51, 0xffff0000, v160
	v_sqrt_f32_e32 v6, v1
	v_max_f32_e32 v1, 0, v7
	v_lshlrev_b32_e32 v62, 16, v161
	v_and_b32_e32 v63, 0xffff0000, v161
	v_sqrt_f32_e32 v7, v1
	v_max_f32_e32 v1, 0, v2
	v_pk_mul_f32 v[6:7], v[6:7], v[48:49]
	v_pk_mul_f32 v[48:49], v[6:7], v[50:51]
	v_pk_mul_f32 v[6:7], v[16:17], v[70:71]
	v_lshlrev_b32_e32 v16, 16, v158
	v_and_b32_e32 v17, 0xffff0000, v158
	v_pk_fma_f32 v[48:49], v[20:21], v[66:67], v[48:49]
	v_lshlrev_b32_e32 v20, 16, v162
	v_and_b32_e32 v21, 0xffff0000, v162
	s_nop 0
	v_sqrt_f32_e32 v2, v1
	v_max_f32_e32 v1, 0, v3
	v_sqrt_f32_e32 v3, v1
	s_nop 0
	v_pk_mul_f32 v[2:3], v[2:3], v[38:39]
	s_nop 0
	v_pk_mul_f32 v[38:39], v[2:3], v[62:63]
	v_pk_mul_f32 v[2:3], v[18:19], v[66:67]
	v_pk_fma_f32 v[50:51], v[10:11], v[70:71], v[38:39]
	v_lshlrev_b32_e32 v10, 16, v154
	v_and_b32_e32 v11, 0xffff0000, v154
	v_pk_mul_f32 v[10:11], v[32:33], v[10:11]
	v_lshlrev_b32_e32 v4, 16, v155
	v_mul_f32_e32 v1, 0x3fb8aa3b, v10
	v_exp_f32_e32 v10, v1
	v_mul_f32_e32 v1, 0x3fb8aa3b, v11
	v_exp_f32_e32 v11, v1
	v_and_b32_e32 v5, 0xffff0000, v155
	v_pk_mul_f32 v[4:5], v[30:31], v[4:5]
	v_xor_b32_e32 v62, 0x80000000, v10
	v_mul_f32_e32 v1, 0x3fb8aa3b, v4
	v_xor_b32_e32 v63, 0x80000000, v11
	v_exp_f32_e32 v4, v1
	v_mul_f32_e32 v1, 0x3fb8aa3b, v5
	v_pk_fma_f32 v[62:63], v[62:63], v[10:11], 1.0 op_sel_hi:[1,1,0]
	v_exp_f32_e32 v5, v1
	v_max_f32_e32 v1, 0, v62
	v_lshlrev_b32_e32 v18, 16, v159
	v_and_b32_e32 v19, 0xffff0000, v159
	v_xor_b32_e32 v41, 0x80000000, v5
	v_xor_b32_e32 v40, 0x80000000, v4
	v_pk_fma_f32 v[40:41], v[40:41], v[4:5], 1.0 op_sel_hi:[1,1,0]
	v_lshlrev_b32_e32 v38, 16, v163
	v_and_b32_e32 v39, 0xffff0000, v163
	v_sqrt_f32_e32 v62, v1
	v_max_f32_e32 v1, 0, v63
	v_sqrt_f32_e32 v63, v1
	v_max_f32_e32 v1, 0, v40
	v_pk_mul_f32 v[16:17], v[62:63], v[16:17]
	v_pk_mul_f32 v[16:17], v[16:17], v[20:21]
	v_pk_mul_f32 v[20:21], v[14:15], v[10:11]
	v_pk_fma_f32 v[36:37], v[36:37], v[10:11], v[16:17]
	v_sqrt_f32_e32 v40, v1
	v_max_f32_e32 v1, 0, v41
	v_sqrt_f32_e32 v41, v1
	s_nop 0
	v_pk_mul_f32 v[18:19], v[40:41], v[18:19]
	s_nop 0
	v_pk_mul_f32 v[18:19], v[18:19], v[38:39]
	v_pk_mul_f32 v[38:39], v[12:13], v[4:5]
	v_pk_fma_f32 v[40:41], v[8:9], v[4:5], v[18:19]
	s_waitcnt vmcnt(2)
; __device__ __forceinline__ f32x4 unpack4(u32x2 u) { return (f32x4){__uint_as_float(u.x << 16), __uint_as_float(u.x & 0xffff0000u), __uint_as_float(u.y << 16), __uint_as_float(u.y & 0xffff0000u)}; }
; template <int ph>
; __device__ __forceinline__ void run_phase(const Args& args, LAS unsigned char* lds, const int G, const int bx, const bool fin = true) {
;     ...
; #pragma unroll 8
;                 for (int t = 0; t < 32; ++t) { const size_t o = base + (size_t)t * D;
;                     const u32x4 gr = *(const u32x4*)(GR + o), gi = *(const u32x4*)(GI + o), xc = *(const u32x4*)(XC + o);
;                     f32x4 a, bb;
;                     lru_ab(unpack4((u32x2){gr.x, gr.y}), unpack4((u32x2){gi.x, gi.y}), unpack4((u32x2){xc.x, xc.y}), sp0, a, bb); A0 = A0 * a; B0 = a * B0 + bb;
;                     lru_ab(unpack4((u32x2){gr.z, gr.w}), unpack4((u32x2){gi.z, gi.w}), unpack4((u32x2){xc.z, xc.w}), sp1, a, bb); A1 = A1 * a; B1 = a * B1 + bb; }
;                 sA[(seg * 8 + l8) * 2] = A0; sA[(seg * 8 + l8) * 2 + 1] = A1; sB[(seg * 8 + l8) * 2] = B0; sB[(seg * 8 + l8) * 2 + 1] = B1;
;                 __syncthreads();
;                 f32x4 h0 = (f32x4){0.f, 0.f, 0.f, 0.f}, h1 = h0;
;                 for (int s2 = 0; s2 < seg; ++s2) { h0 = sA[(s2 * 8 + l8) * 2] * h0 + sB[(s2 * 8 + l8) * 2]; h1 = sA[(s2 * 8 + l8) * 2 + 1] * h1 + sB[(s2 * 8 + l8) * 2 + 1]; }
	v_lshlrev_b32_e32 v4, 16, v164
	v_and_b32_e32 v5, 0xffff0000, v164
	v_pk_mul_f32 v[4:5], v[28:29], v[4:5]
	v_lshlrev_b32_e32 v16, 16, v165
	v_mul_f32_e32 v1, 0x3fb8aa3b, v4
	v_exp_f32_e32 v46, v1
	v_mul_f32_e32 v1, 0x3fb8aa3b, v5
	v_exp_f32_e32 v47, v1
	v_and_b32_e32 v17, 0xffff0000, v165
	v_pk_mul_f32 v[16:17], v[26:27], v[16:17]
	v_xor_b32_e32 v62, 0x80000000, v46
	v_mul_f32_e32 v1, 0x3fb8aa3b, v16
	v_xor_b32_e32 v63, 0x80000000, v47
	v_exp_f32_e32 v4, v1
	v_mul_f32_e32 v1, 0x3fb8aa3b, v17
	v_pk_fma_f32 v[62:63], v[62:63], v[46:47], 1.0 op_sel_hi:[1,1,0]
	v_exp_f32_e32 v5, v1
	v_max_f32_e32 v1, 0, v62
	v_xor_b32_e32 v17, 0x80000000, v5
	v_xor_b32_e32 v16, 0x80000000, v4
	v_pk_fma_f32 v[16:17], v[16:17], v[4:5], 1.0 op_sel_hi:[1,1,0]
	s_waitcnt vmcnt(1)
	v_lshlrev_b32_e32 v42, 16, v168
	v_and_b32_e32 v43, 0xffff0000, v168
	v_lshlrev_b32_e32 v12, 16, v169
	v_and_b32_e32 v13, 0xffff0000, v169
	s_waitcnt vmcnt(0)
	v_lshlrev_b32_e32 v44, 16, v172
	v_and_b32_e32 v45, 0xffff0000, v172
	v_sqrt_f32_e32 v62, v1
	v_max_f32_e32 v1, 0, v63
	v_lshlrev_b32_e32 v8, 16, v173
	v_and_b32_e32 v9, 0xffff0000, v173
	v_sqrt_f32_e32 v63, v1
	v_max_f32_e32 v1, 0, v16
	v_sqrt_f32_e32 v16, v1
	v_max_f32_e32 v1, 0, v17
	v_sqrt_f32_e32 v17, v1
	s_nop 0
	v_pk_mul_f32 v[12:13], v[16:17], v[12:13]
	v_pk_mul_f32 v[16:17], v[62:63], v[42:43]
	v_pk_mul_f32 v[12:13], v[12:13], v[8:9]
	v_pk_mul_f32 v[16:17], v[16:17], v[44:45]
	v_pk_mul_f32 v[8:9], v[6:7], v[4:5]
	v_pk_mul_f32 v[6:7], v[2:3], v[46:47]
	v_pk_fma_f32 v[2:3], v[48:49], v[46:47], v[16:17]
	v_lshlrev_b32_e32 v16, 16, v166
	v_and_b32_e32 v17, 0xffff0000, v166
	v_pk_fma_f32 v[4:5], v[50:51], v[4:5], v[12:13]
	v_lshlrev_b32_e32 v12, 16, v170
	v_and_b32_e32 v13, 0xffff0000, v170
	v_lshlrev_b32_e32 v42, 16, v171
	v_and_b32_e32 v43, 0xffff0000, v171
	v_pk_mul_f32 v[14:15], v[32:33], v[16:17]
	v_lshlrev_b32_e32 v44, 16, v167
	v_mul_f32_e32 v1, 0x3fb8aa3b, v14
	v_exp_f32_e32 v14, v1
	v_mul_f32_e32 v1, 0x3fb8aa3b, v15
	v_exp_f32_e32 v15, v1
	v_and_b32_e32 v45, 0xffff0000, v167
	v_pk_mul_f32 v[44:45], v[30:31], v[44:45]
	v_xor_b32_e32 v46, 0x80000000, v14
	v_mul_f32_e32 v1, 0x3fb8aa3b, v44
	v_xor_b32_e32 v47, 0x80000000, v15
	v_exp_f32_e32 v16, v1
	v_mul_f32_e32 v1, 0x3fb8aa3b, v45
	v_pk_fma_f32 v[46:47], v[46:47], v[14:15], 1.0 op_sel_hi:[1,1,0]
	v_exp_f32_e32 v17, v1
	v_max_f32_e32 v1, 0, v46
	v_xor_b32_e32 v45, 0x80000000, v17
	v_xor_b32_e32 v44, 0x80000000, v16
	v_pk_fma_f32 v[44:45], v[44:45], v[16:17], 1.0 op_sel_hi:[1,1,0]
	v_lshlrev_b32_e32 v18, 16, v174
	v_and_b32_e32 v19, 0xffff0000, v174
	v_lshlrev_b32_e32 v10, 16, v175
	v_and_b32_e32 v11, 0xffff0000, v175
	v_sqrt_f32_e32 v46, v1
	v_max_f32_e32 v1, 0, v47
	v_sqrt_f32_e32 v47, v1
	v_max_f32_e32 v1, 0, v44
	v_pk_mul_f32 v[12:13], v[46:47], v[12:13]
	v_pk_mul_f32 v[18:19], v[12:13], v[18:19]
	v_pk_mul_f32 v[12:13], v[38:39], v[16:17]
	v_sqrt_f32_e32 v44, v1
	v_max_f32_e32 v1, 0, v45
	v_sqrt_f32_e32 v45, v1
	s_nop 0
	v_pk_mul_f32 v[42:43], v[44:45], v[42:43]
	s_nop 0
	v_pk_mul_f32 v[42:43], v[42:43], v[10:11]
	v_pk_mul_f32 v[10:11], v[20:21], v[14:15]
	v_pk_fma_f32 v[16:17], v[40:41], v[16:17], v[42:43]
	v_pk_fma_f32 v[14:15], v[36:37], v[14:15], v[18:19]
	s_cbranch_scc0 .LBB0_1061
	ds_write_b128 v53, v[6:9]
	ds_write_b128 v53, v[10:13] offset:16
	ds_write_b128 v53, v[2:5] offset:16384
	ds_write_b128 v53, v[14:17] offset:16400
	v_mov_b32_e32 v9, 0
	v_mov_b32_e32 v8, 0
	v_mov_b32_e32 v7, 0
	v_mov_b32_e32 v6, 0
	v_mov_b32_e32 v5, 0
	v_mov_b32_e32 v4, 0
	v_mov_b32_e32 v3, 0
	v_mov_b32_e32 v2, 0
	s_waitcnt lgkmcnt(0)
	s_barrier
	s_and_saveexec_b64 s[0:1], s[2:3]
	s_cbranch_execz .LBB0_1072
	v_mov_b32_e32 v2, v0
	v_mov_b32_e32 v3, v0
	v_mov_b32_e32 v1, v0
	v_mov_b64_e32 v[8:9], v[2:3]
	v_mov_b64_e32 v[6:7], v[0:1]
	v_mov_b64_e32 v[4:5], v[2:3]
	v_mov_b32_e32 v10, 0
	v_mov_b64_e32 v[2:3], v[0:1]
	s_and_saveexec_b64 s[24:25], s[6:7]
	s_cbranch_execz .LBB0_1067
	v_mov_b32_e32 v2, 0
	s_mov_b32 s10, 0
	s_mov_b64 s[26:27], 0
	v_mov_b32_e32 v1, v56
	v_mov_b32_e32 v3, v2
	v_mov_b32_e32 v4, v2
	v_mov_b32_e32 v5, v2
	v_mov_b32_e32 v6, v2
	v_mov_b32_e32 v7, v2
	v_mov_b32_e32 v8, v2
	v_mov_b32_e32 v9, v2

; __device__ __forceinline__ f32x4 unpack4(u32x2 u) { return (f32x4){__uint_as_float(u.x << 16), __uint_as_float(u.x & 0xffff0000u), __uint_as_float(u.y << 16), __uint_as_float(u.y & 0xffff0000u)}; }
; __device__ __forceinline__ u32x2 pack4(f32x4 v) { u32x2 r; r.x = cvt_pk_bf16(v.x, v.y); r.y = cvt_pk_bf16(v.z, v.w); return r; }
; template <int ph>
; __device__ __forceinline__ void run_phase(const Args& args, LAS unsigned char* lds, const int G, const int bx, const bool fin = true) {
;     ...
; #pragma unroll 8
;                 for (int t = 0; t < 32; ++t) { const size_t o = base + (size_t)t * D;
;                     const u32x4 gr = *(const u32x4*)(GR + o), gi = *(const u32x4*)(GI + o), xc = *(const u32x4*)(XC + o), gg = *(const u32x4*)(GG + o);
;                     f32x4 a, bb;
;                     lru_ab(unpack4((u32x2){gr.x, gr.y}), unpack4((u32x2){gi.x, gi.y}), unpack4((u32x2){xc.x, xc.y}), sp0, a, bb); h0 = a * h0 + bb;
;                     lru_ab(unpack4((u32x2){gr.z, gr.w}), unpack4((u32x2){gi.z, gi.w}), unpack4((u32x2){xc.z, xc.w}), sp1, a, bb); h1 = a * h1 + bb;
;                     const u32x2 w0 = pack4(h0 * unpack4((u32x2){gg.x, gg.y})), w1 = pack4(h1 * unpack4((u32x2){gg.z, gg.w}));
;                     *(u32x4*)(LO + o) = (u32x4){w0.x, w0.y, w1.x, w1.y}; }
.LBB0_1073:
	s_nop 0
	v_lshl_add_u64 v[10:11], v[34:35], 0, s[24:25]
	v_add_co_u32_e32 v200, vcc, 0x10700000, v10
	s_nop 1
	v_addc_co_u32_e32 v201, vcc, 0, v11, vcc
	v_add_co_u32_e32 v212, vcc, 0x16a00000, v10
	s_nop 1
	v_addc_co_u32_e32 v213, vcc, 0, v11, vcc
	v_add_co_u32_e32 v214, vcc, 0x7d80000, v10
	s_nop 1
	v_addc_co_u32_e32 v215, vcc, 0, v11, vcc
	v_add_co_u32_e32 v216, vcc, 0x12800000, v10
	s_nop 1
	v_addc_co_u32_e32 v217, vcc, 0, v11, vcc
	v_add_co_u32_e32 v218, vcc, s52, v10
	s_nop 1
	v_addc_co_u32_e32 v219, vcc, 0, v11, vcc
	v_add_co_u32_e32 v220, vcc, s55, v10
	s_nop 1
	v_addc_co_u32_e32 v221, vcc, 0, v11, vcc
	v_add_co_u32_e32 v222, vcc, s53, v10
	s_nop 1
	v_addc_co_u32_e32 v223, vcc, 0, v11, vcc
	v_add_co_u32_e32 v224, vcc, s56, v10
	s_nop 1
	v_addc_co_u32_e32 v225, vcc, 0, v11, vcc
	v_add_co_u32_e32 v226, vcc, s54, v10
	s_nop 1
	v_addc_co_u32_e32 v227, vcc, 0, v11, vcc
	v_add_co_u32_e32 v230, vcc, s57, v10
	s_nop 1
	v_addc_co_u32_e32 v231, vcc, 0, v11, vcc
	v_add_co_u32_e32 v232, vcc, s75, v10
	s_nop 1
	v_addc_co_u32_e32 v233, vcc, 0, v11, vcc
	v_add_co_u32_e32 v234, vcc, s76, v10
	s_nop 1
	v_addc_co_u32_e32 v235, vcc, 0, v11, vcc
	v_add_co_u32_e32 v236, vcc, s62, v10
	s_nop 1
	v_addc_co_u32_e32 v237, vcc, 0, v11, vcc
	v_add_co_u32_e32 v238, vcc, s63, v10
	s_nop 1
	v_addc_co_u32_e32 v239, vcc, 0, v11, vcc
	v_add_co_u32_e32 v240, vcc, s74, v10
	s_nop 1
	v_addc_co_u32_e32 v241, vcc, 0, v11, vcc
	v_add_co_u32_e32 v242, vcc, s77, v10
	s_nop 1
	v_addc_co_u32_e32 v243, vcc, 0, v11, vcc
	global_load_dwordx4 v[80:83], v[200:201], off
	global_load_dwordx4 v[84:87], v[212:213], off
	global_load_dwordx4 v[88:91], v[214:215], off
	global_load_dwordx4 v[92:95], v[216:217], off
	global_load_dwordx4 v[96:99], v[200:201], off offset:2048
	global_load_dwordx4 v[100:103], v[212:213], off offset:2048
	global_load_dwordx4 v[104:107], v[214:215], off offset:2048
	global_load_dwordx4 v[108:111], v[216:217], off offset:2048
	global_load_dwordx4 v[112:115], v[220:221], off offset:-4096
	global_load_dwordx4 v[116:119], v[224:225], off offset:-4096
	global_load_dwordx4 v[120:123], v[230:231], off offset:-4096
	global_load_dwordx4 v[124:127], v[234:235], off offset:-4096
	global_load_dwordx4 v[128:131], v[218:219], off offset:2048
	global_load_dwordx4 v[132:135], v[222:223], off offset:2048
	global_load_dwordx4 v[136:139], v[226:227], off offset:2048
	global_load_dwordx4 v[140:143], v[232:233], off offset:2048
	global_load_dwordx4 v[144:147], v[220:221], off
	global_load_dwordx4 v[148:151], v[224:225], off
	global_load_dwordx4 v[152:155], v[230:231], off
	global_load_dwordx4 v[156:159], v[234:235], off
	global_load_dwordx4 v[160:163], v[220:221], off offset:2048
	global_load_dwordx4 v[164:167], v[224:225], off offset:2048
	global_load_dwordx4 v[168:171], v[230:231], off offset:2048
	global_load_dwordx4 v[172:175], v[234:235], off offset:2048
	global_load_dwordx4 v[176:179], v[236:237], off
	global_load_dwordx4 v[180:183], v[238:239], off
	global_load_dwordx4 v[184:187], v[240:241], off
	global_load_dwordx4 v[188:191], v[242:243], off
	global_load_dwordx4 v[192:195], v[236:237], off offset:2048
	global_load_dwordx4 v[196:199], v[238:239], off offset:2048
	global_load_dwordx4 v[204:207], v[240:241], off offset:2048
	global_load_dwordx4 v[208:211], v[242:243], off offset:2048
	s_add_u32 s24, s24, 0x4000
	s_nop 0
	s_addc_u32 s25, s25, 0
	s_nop 0
	s_nop 0
	s_cmp_eq_u32 s24, 0x10000
	s_nop 0
	s_waitcnt vmcnt(31)
	v_lshlrev_b32_e32 v50, 16, v80
	v_and_b32_e32 v51, 0xffff0000, v80
	v_pk_mul_f32 v[50:51], v[28:29], v[50:51]
	v_lshlrev_b32_e32 v14, 16, v81
	v_mul_f32_e32 v1, 0x3fb8aa3b, v50
	v_exp_f32_e32 v50, v1
	v_mul_f32_e32 v1, 0x3fb8aa3b, v51
	v_exp_f32_e32 v51, v1
	v_and_b32_e32 v15, 0xffff0000, v81
	v_pk_mul_f32 v[14:15], v[26:27], v[14:15]
	v_xor_b32_e32 v70, 0x80000000, v50
	v_mul_f32_e32 v1, 0x3fb8aa3b, v14
	v_xor_b32_e32 v71, 0x80000000, v51
	v_exp_f32_e32 v14, v1
	v_mul_f32_e32 v1, 0x3fb8aa3b, v15
	v_pk_fma_f32 v[70:71], v[70:71], v[50:51], 1.0 op_sel_hi:[1,1,0]
	v_exp_f32_e32 v15, v1
	v_max_f32_e32 v1, 0, v70
	v_xor_b32_e32 v67, 0x80000000, v15
	v_xor_b32_e32 v66, 0x80000000, v14
	v_pk_fma_f32 v[66:67], v[66:67], v[14:15], 1.0 op_sel_hi:[1,1,0]
	s_waitcnt vmcnt(30)
	v_lshlrev_b32_e32 v62, 16, v84
	v_and_b32_e32 v63, 0xffff0000, v84
	v_lshlrev_b32_e32 v18, 16, v85
	v_and_b32_e32 v19, 0xffff0000, v85
	s_waitcnt vmcnt(29)
	v_lshlrev_b32_e32 v64, 16, v88
	v_and_b32_e32 v65, 0xffff0000, v88
	v_sqrt_f32_e32 v70, v1
	v_max_f32_e32 v1, 0, v71
	v_lshlrev_b32_e32 v36, 16, v89
	v_and_b32_e32 v37, 0xffff0000, v89
	v_sqrt_f32_e32 v71, v1
	v_max_f32_e32 v1, 0, v66
	v_pk_mul_f32 v[62:63], v[70:71], v[62:63]
	v_sqrt_f32_e32 v66, v1
	v_max_f32_e32 v1, 0, v67
	v_sqrt_f32_e32 v67, v1
	s_nop 0
	v_pk_mul_f32 v[18:19], v[66:67], v[18:19]
	s_nop 0
	v_pk_mul_f32 v[18:19], v[18:19], v[36:37]
	v_pk_mul_f32 v[36:37], v[62:63], v[64:65]
	v_pk_fma_f32 v[62:63], v[4:5], v[14:15], v[18:19]
	v_pk_fma_f32 v[50:51], v[2:3], v[50:51], v[36:37]
	v_lshlrev_b32_e32 v2, 16, v82
	v_and_b32_e32 v3, 0xffff0000, v82
	v_pk_mul_f32 v[2:3], v[32:33], v[2:3]
	v_lshlrev_b32_e32 v4, 16, v83
	v_mul_f32_e32 v1, 0x3fb8aa3b, v2
	v_exp_f32_e32 v2, v1
	v_mul_f32_e32 v1, 0x3fb8aa3b, v3
	v_exp_f32_e32 v3, v1
	v_and_b32_e32 v5, 0xffff0000, v83
	v_pk_mul_f32 v[4:5], v[30:31], v[4:5]
	v_lshlrev_b32_e32 v14, 16, v86
	v_and_b32_e32 v15, 0xffff0000, v86
	v_lshlrev_b32_e32 v16, 16, v87
	v_and_b32_e32 v17, 0xffff0000, v87
	v_lshlrev_b32_e32 v18, 16, v90
	v_and_b32_e32 v19, 0xffff0000, v90
	v_lshlrev_b32_e32 v20, 16, v91
	v_and_b32_e32 v21, 0xffff0000, v91
	v_mul_f32_e32 v1, 0x3fb8aa3b, v4
	v_xor_b32_e32 v39, 0x80000000, v3
	v_xor_b32_e32 v38, 0x80000000, v2
	v_exp_f32_e32 v4, v1
	v_mul_f32_e32 v1, 0x3fb8aa3b, v5
	v_pk_fma_f32 v[38:39], v[38:39], v[2:3], 1.0 op_sel_hi:[1,1,0]
	v_exp_f32_e32 v5, v1
	v_max_f32_e32 v1, 0, v38
	v_xor_b32_e32 v37, 0x80000000, v5
	v_xor_b32_e32 v36, 0x80000000, v4
	v_pk_fma_f32 v[36:37], v[36:37], v[4:5], 1.0 op_sel_hi:[1,1,0]
	v_sqrt_f32_e32 v38, v1
	v_max_f32_e32 v1, 0, v39
	v_sqrt_f32_e32 v39, v1
	v_max_f32_e32 v1, 0, v36
	v_pk_mul_f32 v[14:15], v[38:39], v[14:15]
	v_pk_mul_f32 v[14:15], v[14:15], v[18:19]
	v_pk_fma_f32 v[64:65], v[6:7], v[2:3], v[14:15]
	s_waitcnt vmcnt(28)
; __device__ __forceinline__ f32x4 unpack4(u32x2 u) { return (f32x4){__uint_as_float(u.x << 16), __uint_as_float(u.x & 0xffff0000u), __uint_as_float(u.y << 16), __uint_as_float(u.y & 0xffff0000u)}; }
; __device__ __forceinline__ u32x2 pack4(f32x4 v) { u32x2 r; r.x = cvt_pk_bf16(v.x, v.y); r.y = cvt_pk_bf16(v.z, v.w); return r; }
; template <int ph>
; __device__ __forceinline__ void run_phase(const Args& args, LAS unsigned char* lds, const int G, const int bx, const bool fin = true) {
;     ...
; #pragma unroll 8
;                 for (int t = 0; t < 32; ++t) { const size_t o = base + (size_t)t * D;
;                     const u32x4 gr = *(const u32x4*)(GR + o), gi = *(const u32x4*)(GI + o), xc = *(const u32x4*)(XC + o), gg = *(const u32x4*)(GG + o);
;                     f32x4 a, bb;
;                     lru_ab(unpack4((u32x2){gr.x, gr.y}), unpack4((u32x2){gi.x, gi.y}), unpack4((u32x2){xc.x, xc.y}), sp0, a, bb); h0 = a * h0 + bb;
;                     lru_ab(unpack4((u32x2){gr.z, gr.w}), unpack4((u32x2){gi.z, gi.w}), unpack4((u32x2){xc.z, xc.w}), sp1, a, bb); h1 = a * h1 + bb;
;                     const u32x2 w0 = pack4(h0 * unpack4((u32x2){gg.x, gg.y})), w1 = pack4(h1 * unpack4((u32x2){gg.z, gg.w}));
;                     *(u32x4*)(LO + o) = (u32x4){w0.x, w0.y, w1.x, w1.y}; }
	v_lshlrev_b32_e32 v2, 16, v92
	v_and_b32_e32 v3, 0xffff0000, v92
	v_pk_mul_f32 v[2:3], v[50:51], v[2:3]
	v_lshlrev_b32_e32 v6, 16, v95
	v_sqrt_f32_e32 v36, v1
	v_max_f32_e32 v1, 0, v37
	v_cvt_pk_bf16_f32 v2, v2, v3
	v_and_b32_e32 v7, 0xffff0000, v95
	v_sqrt_f32_e32 v37, v1
	s_nop 0
	v_pk_mul_f32 v[16:17], v[36:37], v[16:17]
	s_nop 0
	v_pk_mul_f32 v[16:17], v[16:17], v[20:21]
	s_nop 0
	v_pk_fma_f32 v[8:9], v[8:9], v[4:5], v[16:17]
	v_lshlrev_b32_e32 v4, 16, v93
	v_and_b32_e32 v5, 0xffff0000, v93
	v_pk_mul_f32 v[4:5], v[62:63], v[4:5]
	v_pk_mul_f32 v[6:7], v[8:9], v[6:7]
	v_cvt_pk_bf16_f32 v3, v4, v5
	v_lshlrev_b32_e32 v4, 16, v94
	v_and_b32_e32 v5, 0xffff0000, v94
	v_pk_mul_f32 v[4:5], v[64:65], v[4:5]
	s_nop 0
	v_cvt_pk_bf16_f32 v4, v4, v5
	v_cvt_pk_bf16_f32 v5, v6, v7
	global_store_dwordx4 v[212:213], v[2:5], off
	s_nop 0
	s_waitcnt vmcnt(28)
	v_lshlrev_b32_e32 v2, 16, v96
	v_and_b32_e32 v3, 0xffff0000, v96
	v_pk_mul_f32 v[2:3], v[28:29], v[2:3]
	v_lshlrev_b32_e32 v4, 16, v97
	v_mul_f32_e32 v1, 0x3fb8aa3b, v2
	v_exp_f32_e32 v2, v1
	v_mul_f32_e32 v1, 0x3fb8aa3b, v3
	v_exp_f32_e32 v3, v1
	v_and_b32_e32 v5, 0xffff0000, v97
	v_pk_mul_f32 v[4:5], v[26:27], v[4:5]
	v_xor_b32_e32 v46, 0x80000000, v2
	v_mul_f32_e32 v1, 0x3fb8aa3b, v4
	v_xor_b32_e32 v47, 0x80000000, v3
	v_exp_f32_e32 v4, v1
	v_mul_f32_e32 v1, 0x3fb8aa3b, v5
	v_pk_fma_f32 v[46:47], v[46:47], v[2:3], 1.0 op_sel_hi:[1,1,0]
	v_exp_f32_e32 v5, v1
	v_max_f32_e32 v1, 0, v46
	v_xor_b32_e32 v45, 0x80000000, v5
	v_xor_b32_e32 v44, 0x80000000, v4
	v_pk_fma_f32 v[44:45], v[44:45], v[4:5], 1.0 op_sel_hi:[1,1,0]
	s_waitcnt vmcnt(27)
	v_lshlrev_b32_e32 v40, 16, v100
	v_and_b32_e32 v41, 0xffff0000, v100
	v_lshlrev_b32_e32 v14, 16, v101
	v_and_b32_e32 v15, 0xffff0000, v101
	s_waitcnt vmcnt(26)
	v_lshlrev_b32_e32 v42, 16, v104
	v_and_b32_e32 v43, 0xffff0000, v104
	v_sqrt_f32_e32 v46, v1
	v_max_f32_e32 v1, 0, v47
	v_lshlrev_b32_e32 v18, 16, v105
	v_and_b32_e32 v19, 0xffff0000, v105
	v_sqrt_f32_e32 v47, v1
	v_max_f32_e32 v1, 0, v44
	v_pk_mul_f32 v[40:41], v[46:47], v[40:41]
	v_sqrt_f32_e32 v44, v1
	v_max_f32_e32 v1, 0, v45
	v_sqrt_f32_e32 v45, v1
	s_nop 0
	v_pk_mul_f32 v[14:15], v[44:45], v[14:15]
	s_nop 0
	v_pk_mul_f32 v[14:15], v[14:15], v[18:19]
	v_pk_mul_f32 v[18:19], v[40:41], v[42:43]
	v_pk_fma_f32 v[4:5], v[62:63], v[4:5], v[14:15]
	v_lshlrev_b32_e32 v14, 16, v98
	v_and_b32_e32 v15, 0xffff0000, v98
	v_pk_mul_f32 v[14:15], v[32:33], v[14:15]
	v_lshlrev_b32_e32 v6, 16, v99
	v_mul_f32_e32 v1, 0x3fb8aa3b, v14
	v_exp_f32_e32 v14, v1
	v_mul_f32_e32 v1, 0x3fb8aa3b, v15
	v_exp_f32_e32 v15, v1
	v_and_b32_e32 v7, 0xffff0000, v99
	v_pk_mul_f32 v[6:7], v[30:31], v[6:7]
	v_xor_b32_e32 v44, 0x80000000, v14
	v_mul_f32_e32 v1, 0x3fb8aa3b, v6
	v_xor_b32_e32 v45, 0x80000000, v15
	v_exp_f32_e32 v42, v1
	v_mul_f32_e32 v1, 0x3fb8aa3b, v7
	v_pk_fma_f32 v[44:45], v[44:45], v[14:15], 1.0 op_sel_hi:[1,1,0]
	v_exp_f32_e32 v43, v1
	v_max_f32_e32 v1, 0, v44
	v_xor_b32_e32 v7, 0x80000000, v43
	v_xor_b32_e32 v6, 0x80000000, v42
	v_pk_fma_f32 v[6:7], v[6:7], v[42:43], 1.0 op_sel_hi:[1,1,0]
	v_pk_fma_f32 v[2:3], v[50:51], v[2:3], v[18:19]
	v_lshlrev_b32_e32 v18, 16, v102
	v_and_b32_e32 v19, 0xffff0000, v102
	v_lshlrev_b32_e32 v16, 16, v103
	v_and_b32_e32 v17, 0xffff0000, v103
	v_lshlrev_b32_e32 v40, 16, v106
	v_sqrt_f32_e32 v44, v1
	v_max_f32_e32 v1, 0, v45
	v_and_b32_e32 v41, 0xffff0000, v106
	v_lshlrev_b32_e32 v20, 16, v107
	v_and_b32_e32 v21, 0xffff0000, v107
	v_sqrt_f32_e32 v45, v1
	v_max_f32_e32 v1, 0, v6
	v_pk_mul_f32 v[18:19], v[44:45], v[18:19]
	v_sqrt_f32_e32 v6, v1
	v_max_f32_e32 v1, 0, v7
	v_sqrt_f32_e32 v7, v1
	s_nop 0
	v_pk_mul_f32 v[6:7], v[6:7], v[16:17]
	s_nop 0
	v_pk_mul_f32 v[16:17], v[6:7], v[20:21]
	v_pk_mul_f32 v[6:7], v[18:19], v[40:41]
	v_pk_fma_f32 v[8:9], v[8:9], v[42:43], v[16:17]
	v_pk_fma_f32 v[6:7], v[64:65], v[14:15], v[6:7]
	s_waitcnt vmcnt(25)
	v_lshlrev_b32_e32 v14, 16, v108
	v_and_b32_e32 v15, 0xffff0000, v108
	v_lshlrev_b32_e32 v16, 16, v109
	v_and_b32_e32 v17, 0xffff0000, v109
	v_pk_mul_f32 v[16:17], v[4:5], v[16:17]
	v_pk_mul_f32 v[14:15], v[2:3], v[14:15]
	v_lshlrev_b32_e32 v18, 16, v111
	v_cvt_pk_bf16_f32 v14, v14, v15
	v_cvt_pk_bf16_f32 v15, v16, v17
	v_lshlrev_b32_e32 v16, 16, v110
	v_and_b32_e32 v17, 0xffff0000, v110
	v_and_b32_e32 v19, 0xffff0000, v111
	v_pk_mul_f32 v[18:19], v[8:9], v[18:19]
	v_pk_mul_f32 v[16:17], v[6:7], v[16:17]
	v_cvt_pk_bf16_f32 v16, v16, v17
	v_cvt_pk_bf16_f32 v17, v18, v19
	global_store_dwordx4 v[212:213], v[14:17], off offset:2048
	s_nop 1
	s_nop 1
	s_nop 1
	s_nop 1
	s_nop 0
	s_waitcnt vmcnt(25)
	v_lshlrev_b32_e32 v70, 16, v112
	v_and_b32_e32 v71, 0xffff0000, v112
	v_pk_mul_f32 v[70:71], v[28:29], v[70:71]
	v_lshlrev_b32_e32 v38, 16, v113
	v_mul_f32_e32 v1, 0x3fb8aa3b, v70
	v_exp_f32_e32 v70, v1
	v_mul_f32_e32 v1, 0x3fb8aa3b, v71
	v_exp_f32_e32 v71, v1
	v_and_b32_e32 v39, 0xffff0000, v113
	v_pk_mul_f32 v[38:39], v[26:27], v[38:39]
	s_nop 0
	v_mul_f32_e32 v1, 0x3fb8aa3b, v38
	v_xor_b32_e32 v79, 0x80000000, v71
	v_xor_b32_e32 v78, 0x80000000, v70
	v_exp_f32_e32 v38, v1
	v_mul_f32_e32 v1, 0x3fb8aa3b, v39
	v_pk_fma_f32 v[78:79], v[78:79], v[70:71], 1.0 op_sel_hi:[1,1,0]
	v_exp_f32_e32 v39, v1
	v_max_f32_e32 v1, 0, v78
	v_xor_b32_e32 v77, 0x80000000, v39
	v_xor_b32_e32 v76, 0x80000000, v38
	v_pk_fma_f32 v[76:77], v[76:77], v[38:39], 1.0 op_sel_hi:[1,1,0]
	s_waitcnt vmcnt(24)
	v_lshlrev_b32_e32 v72, 16, v116
	v_and_b32_e32 v73, 0xffff0000, v116
	v_lshlrev_b32_e32 v42, 16, v117
	v_and_b32_e32 v43, 0xffff0000, v117
	s_waitcnt vmcnt(23)
; __device__ __forceinline__ f32x4 unpack4(u32x2 u) { return (f32x4){__uint_as_float(u.x << 16), __uint_as_float(u.x & 0xffff0000u), __uint_as_float(u.y << 16), __uint_as_float(u.y & 0xffff0000u)}; }
; __device__ __forceinline__ u32x2 pack4(f32x4 v) { u32x2 r; r.x = cvt_pk_bf16(v.x, v.y); r.y = cvt_pk_bf16(v.z, v.w); return r; }
; template <int ph>
; __device__ __forceinline__ void run_phase(const Args& args, LAS unsigned char* lds, const int G, const int bx, const bool fin = true) {
;     ...
;             auto lru_ab = [](f32x4 gr, f32x4 gi, f32x4 xc, f32x4 sp, f32x4& a, f32x4& bb) {
;                 const f32x4 la = gr * sp; a = (f32x4){__expf(la[0]), __expf(la[1]), __expf(la[2]), __expf(la[3])};
;                 const f32x4 om = (f32x4){1.f, 1.f, 1.f, 1.f} - a * a;
;                 bb = (f32x4){sqrtf(fmaxf(om[0], 0.f)), sqrtf(fmaxf(om[1], 0.f)), sqrtf(fmaxf(om[2], 0.f)), sqrtf(fmaxf(om[3], 0.f))} * gi * xc; };
;     ...
; #pragma unroll 8
;                 for (int t = 0; t < 32; ++t) { const size_t o = base + (size_t)t * D;
;                     const u32x4 gr = *(const u32x4*)(GR + o), gi = *(const u32x4*)(GI + o), xc = *(const u32x4*)(XC + o), gg = *(const u32x4*)(GG + o);
;                     f32x4 a, bb;
;                     lru_ab(unpack4((u32x2){gr.x, gr.y}), unpack4((u32x2){gi.x, gi.y}), unpack4((u32x2){xc.x, xc.y}), sp0, a, bb); h0 = a * h0 + bb;
;                     lru_ab(unpack4((u32x2){gr.z, gr.w}), unpack4((u32x2){gi.z, gi.w}), unpack4((u32x2){xc.z, xc.w}), sp1, a, bb); h1 = a * h1 + bb;
;                     const u32x2 w0 = pack4(h0 * unpack4((u32x2){gg.x, gg.y})), w1 = pack4(h1 * unpack4((u32x2){gg.z, gg.w}));
;                     *(u32x4*)(LO + o) = (u32x4){w0.x, w0.y, w1.x, w1.y}; }
	v_lshlrev_b32_e32 v74, 16, v120
	v_sqrt_f32_e32 v78, v1
	v_max_f32_e32 v1, 0, v79
	v_and_b32_e32 v75, 0xffff0000, v120
	v_lshlrev_b32_e32 v46, 16, v121
	v_and_b32_e32 v47, 0xffff0000, v121
	v_sqrt_f32_e32 v79, v1
	v_max_f32_e32 v1, 0, v76
	v_pk_mul_f32 v[72:73], v[78:79], v[72:73]
	v_sqrt_f32_e32 v76, v1
	v_max_f32_e32 v1, 0, v77
	v_sqrt_f32_e32 v77, v1
	s_nop 0
	v_pk_mul_f32 v[42:43], v[76:77], v[42:43]
	s_nop 0
	v_pk_mul_f32 v[42:43], v[42:43], v[46:47]
	v_pk_mul_f32 v[46:47], v[72:73], v[74:75]
	s_nop 0
	v_pk_fma_f32 v[46:47], v[2:3], v[70:71], v[46:47]
	v_lshlrev_b32_e32 v2, 16, v114
	v_and_b32_e32 v3, 0xffff0000, v114
	v_pk_mul_f32 v[2:3], v[32:33], v[2:3]
	v_pk_fma_f32 v[70:71], v[4:5], v[38:39], v[42:43]
	v_mul_f32_e32 v1, 0x3fb8aa3b, v2
	v_exp_f32_e32 v2, v1
	v_mul_f32_e32 v1, 0x3fb8aa3b, v3
	v_exp_f32_e32 v3, v1
	v_lshlrev_b32_e32 v4, 16, v115
	v_and_b32_e32 v5, 0xffff0000, v115
	v_pk_mul_f32 v[4:5], v[30:31], v[4:5]
	v_xor_b32_e32 v73, 0x80000000, v3
	v_mul_f32_e32 v1, 0x3fb8aa3b, v4
	v_xor_b32_e32 v72, 0x80000000, v2
	v_exp_f32_e32 v4, v1
	v_mul_f32_e32 v1, 0x3fb8aa3b, v5
	v_pk_fma_f32 v[72:73], v[72:73], v[2:3], 1.0 op_sel_hi:[1,1,0]
	v_exp_f32_e32 v5, v1
	v_max_f32_e32 v1, 0, v72
	v_lshlrev_b32_e32 v38, 16, v118
	v_and_b32_e32 v39, 0xffff0000, v118
	v_lshlrev_b32_e32 v40, 16, v119
	v_and_b32_e32 v41, 0xffff0000, v119
	v_lshlrev_b32_e32 v42, 16, v122
	v_and_b32_e32 v43, 0xffff0000, v122
	v_lshlrev_b32_e32 v44, 16, v123
	v_and_b32_e32 v45, 0xffff0000, v123
	v_xor_b32_e32 v49, 0x80000000, v5
	v_sqrt_f32_e32 v72, v1
	v_max_f32_e32 v1, 0, v73
	v_xor_b32_e32 v48, 0x80000000, v4
	v_pk_fma_f32 v[48:49], v[48:49], v[4:5], 1.0 op_sel_hi:[1,1,0]
	v_sqrt_f32_e32 v73, v1
	v_max_f32_e32 v1, 0, v48
	v_pk_mul_f32 v[38:39], v[72:73], v[38:39]
	v_pk_mul_f32 v[38:39], v[38:39], v[42:43]
	v_sqrt_f32_e32 v48, v1
	v_max_f32_e32 v1, 0, v49
	v_sqrt_f32_e32 v49, v1
	s_nop 0
	v_pk_mul_f32 v[40:41], v[48:49], v[40:41]
	s_nop 0
	v_pk_mul_f32 v[40:41], v[40:41], v[44:45]
	v_pk_fma_f32 v[44:45], v[6:7], v[2:3], v[38:39]
	v_pk_fma_f32 v[48:49], v[8:9], v[4:5], v[40:41]
	s_waitcnt vmcnt(22)
	v_lshlrev_b32_e32 v2, 16, v124
	v_and_b32_e32 v3, 0xffff0000, v124
	v_lshlrev_b32_e32 v4, 16, v125
	v_and_b32_e32 v5, 0xffff0000, v125
	v_pk_mul_f32 v[4:5], v[70:71], v[4:5]
	v_pk_mul_f32 v[2:3], v[46:47], v[2:3]
	v_lshlrev_b32_e32 v6, 16, v127
	v_cvt_pk_bf16_f32 v2, v2, v3
	v_cvt_pk_bf16_f32 v3, v4, v5
	v_lshlrev_b32_e32 v4, 16, v126
	v_and_b32_e32 v5, 0xffff0000, v126
	v_and_b32_e32 v7, 0xffff0000, v127
	v_pk_mul_f32 v[6:7], v[48:49], v[6:7]
	v_pk_mul_f32 v[4:5], v[44:45], v[4:5]
	s_nop 0
	v_cvt_pk_bf16_f32 v4, v4, v5
	v_cvt_pk_bf16_f32 v5, v6, v7
	global_store_dwordx4 v[224:225], v[2:5], off offset:-4096
	s_nop 0
	s_waitcnt vmcnt(22)
	v_lshlrev_b32_e32 v50, 16, v128
	v_and_b32_e32 v51, 0xffff0000, v128
	v_pk_mul_f32 v[50:51], v[28:29], v[50:51]
	v_lshlrev_b32_e32 v2, 16, v129
	v_mul_f32_e32 v1, 0x3fb8aa3b, v50
	v_exp_f32_e32 v50, v1
	v_mul_f32_e32 v1, 0x3fb8aa3b, v51
	v_exp_f32_e32 v51, v1
	v_and_b32_e32 v3, 0xffff0000, v129
	v_pk_mul_f32 v[2:3], v[26:27], v[2:3]
	v_xor_b32_e32 v72, 0x80000000, v50
	v_mul_f32_e32 v1, 0x3fb8aa3b, v2
	v_xor_b32_e32 v73, 0x80000000, v51
	v_exp_f32_e32 v2, v1
	v_mul_f32_e32 v1, 0x3fb8aa3b, v3
	v_pk_fma_f32 v[72:73], v[72:73], v[50:51], 1.0 op_sel_hi:[1,1,0]
	v_exp_f32_e32 v3, v1
	v_max_f32_e32 v1, 0, v72
	v_xor_b32_e32 v67, 0x80000000, v3
	v_xor_b32_e32 v66, 0x80000000, v2
	v_pk_fma_f32 v[66:67], v[66:67], v[2:3], 1.0 op_sel_hi:[1,1,0]
	s_waitcnt vmcnt(21)
	v_lshlrev_b32_e32 v62, 16, v132
	v_and_b32_e32 v63, 0xffff0000, v132
	v_lshlrev_b32_e32 v6, 16, v133
	v_and_b32_e32 v7, 0xffff0000, v133
	s_waitcnt vmcnt(20)
	v_lshlrev_b32_e32 v64, 16, v136
	v_and_b32_e32 v65, 0xffff0000, v136
	v_sqrt_f32_e32 v72, v1
	v_max_f32_e32 v1, 0, v73
	v_lshlrev_b32_e32 v36, 16, v137
	v_and_b32_e32 v37, 0xffff0000, v137
	v_sqrt_f32_e32 v73, v1
	v_max_f32_e32 v1, 0, v66
	v_pk_mul_f32 v[62:63], v[72:73], v[62:63]
	v_sqrt_f32_e32 v66, v1
	v_max_f32_e32 v1, 0, v67
	v_sqrt_f32_e32 v67, v1
	s_nop 0
	v_pk_mul_f32 v[6:7], v[66:67], v[6:7]
	s_nop 0
	v_pk_mul_f32 v[6:7], v[6:7], v[36:37]
	v_pk_mul_f32 v[36:37], v[62:63], v[64:65]
	s_nop 0
	v_pk_fma_f32 v[46:47], v[46:47], v[50:51], v[36:37]
	v_pk_fma_f32 v[50:51], v[70:71], v[2:3], v[6:7]
	v_lshlrev_b32_e32 v2, 16, v130
	v_and_b32_e32 v3, 0xffff0000, v130
	v_pk_mul_f32 v[2:3], v[32:33], v[2:3]
	v_lshlrev_b32_e32 v4, 16, v131
	v_mul_f32_e32 v1, 0x3fb8aa3b, v2
	v_exp_f32_e32 v2, v1
	v_mul_f32_e32 v1, 0x3fb8aa3b, v3
	v_exp_f32_e32 v3, v1
	v_and_b32_e32 v5, 0xffff0000, v131
	v_pk_mul_f32 v[4:5], v[30:31], v[4:5]
	v_xor_b32_e32 v64, 0x80000000, v2
	v_mul_f32_e32 v1, 0x3fb8aa3b, v4
	v_xor_b32_e32 v65, 0x80000000, v3
	v_exp_f32_e32 v4, v1
	v_mul_f32_e32 v1, 0x3fb8aa3b, v5
	v_pk_fma_f32 v[64:65], v[64:65], v[2:3], 1.0 op_sel_hi:[1,1,0]
	v_exp_f32_e32 v5, v1
	v_max_f32_e32 v1, 0, v64
	v_xor_b32_e32 v63, 0x80000000, v5
	v_xor_b32_e32 v62, 0x80000000, v4
	v_pk_fma_f32 v[62:63], v[62:63], v[4:5], 1.0 op_sel_hi:[1,1,0]
	v_lshlrev_b32_e32 v6, 16, v134
	v_and_b32_e32 v7, 0xffff0000, v134
	v_lshlrev_b32_e32 v8, 16, v135
	v_and_b32_e32 v9, 0xffff0000, v135
	v_lshlrev_b32_e32 v36, 16, v138
	v_and_b32_e32 v37, 0xffff0000, v138
	v_sqrt_f32_e32 v64, v1
	v_max_f32_e32 v1, 0, v65
	v_lshlrev_b32_e32 v38, 16, v139
	v_and_b32_e32 v39, 0xffff0000, v139
	v_sqrt_f32_e32 v65, v1
	v_max_f32_e32 v1, 0, v62
	v_pk_mul_f32 v[6:7], v[64:65], v[6:7]
	v_pk_mul_f32 v[6:7], v[6:7], v[36:37]
	v_pk_fma_f32 v[44:45], v[44:45], v[2:3], v[6:7]
	s_waitcnt vmcnt(19)
; __device__ __forceinline__ f32x4 unpack4(u32x2 u) { return (f32x4){__uint_as_float(u.x << 16), __uint_as_float(u.x & 0xffff0000u), __uint_as_float(u.y << 16), __uint_as_float(u.y & 0xffff0000u)}; }
; __device__ __forceinline__ u32x2 pack4(f32x4 v) { u32x2 r; r.x = cvt_pk_bf16(v.x, v.y); r.y = cvt_pk_bf16(v.z, v.w); return r; }
; template <int ph>
; __device__ __forceinline__ void run_phase(const Args& args, LAS unsigned char* lds, const int G, const int bx, const bool fin = true) {
;     ...
;             auto lru_ab = [](f32x4 gr, f32x4 gi, f32x4 xc, f32x4 sp, f32x4& a, f32x4& bb) {
;                 const f32x4 la = gr * sp; a = (f32x4){__expf(la[0]), __expf(la[1]), __expf(la[2]), __expf(la[3])};
;                 const f32x4 om = (f32x4){1.f, 1.f, 1.f, 1.f} - a * a;
;                 bb = (f32x4){sqrtf(fmaxf(om[0], 0.f)), sqrtf(fmaxf(om[1], 0.f)), sqrtf(fmaxf(om[2], 0.f)), sqrtf(fmaxf(om[3], 0.f))} * gi * xc; };
;     ...
; #pragma unroll 8
;                 for (int t = 0; t < 32; ++t) { const size_t o = base + (size_t)t * D;
;                     const u32x4 gr = *(const u32x4*)(GR + o), gi = *(const u32x4*)(GI + o), xc = *(const u32x4*)(XC + o), gg = *(const u32x4*)(GG + o);
;                     f32x4 a, bb;
;                     lru_ab(unpack4((u32x2){gr.x, gr.y}), unpack4((u32x2){gi.x, gi.y}), unpack4((u32x2){xc.x, xc.y}), sp0, a, bb); h0 = a * h0 + bb;
;                     lru_ab(unpack4((u32x2){gr.z, gr.w}), unpack4((u32x2){gi.z, gi.w}), unpack4((u32x2){xc.z, xc.w}), sp1, a, bb); h1 = a * h1 + bb;
;                     const u32x2 w0 = pack4(h0 * unpack4((u32x2){gg.x, gg.y})), w1 = pack4(h1 * unpack4((u32x2){gg.z, gg.w}));
;                     *(u32x4*)(LO + o) = (u32x4){w0.x, w0.y, w1.x, w1.y}; }
	v_lshlrev_b32_e32 v2, 16, v140
	v_and_b32_e32 v3, 0xffff0000, v140
	v_pk_mul_f32 v[2:3], v[46:47], v[2:3]
	v_lshlrev_b32_e32 v6, 16, v143
	v_sqrt_f32_e32 v62, v1
	v_max_f32_e32 v1, 0, v63
	v_cvt_pk_bf16_f32 v2, v2, v3
	v_and_b32_e32 v7, 0xffff0000, v143
	v_sqrt_f32_e32 v63, v1
	s_nop 0
	v_pk_mul_f32 v[8:9], v[62:63], v[8:9]
	s_nop 0
	v_pk_mul_f32 v[8:9], v[8:9], v[38:39]
	s_nop 0
	v_pk_fma_f32 v[48:49], v[48:49], v[4:5], v[8:9]
	v_lshlrev_b32_e32 v4, 16, v141
	v_and_b32_e32 v5, 0xffff0000, v141
	v_pk_mul_f32 v[4:5], v[50:51], v[4:5]
	v_pk_mul_f32 v[6:7], v[48:49], v[6:7]
	v_cvt_pk_bf16_f32 v3, v4, v5
	v_lshlrev_b32_e32 v4, 16, v142
	v_and_b32_e32 v5, 0xffff0000, v142
	v_pk_mul_f32 v[4:5], v[44:45], v[4:5]
	s_nop 0
	v_cvt_pk_bf16_f32 v4, v4, v5
	v_cvt_pk_bf16_f32 v5, v6, v7
	global_store_dwordx4 v[222:223], v[2:5], off offset:2048
	s_nop 0
	s_waitcnt vmcnt(19)
	v_lshlrev_b32_e32 v20, 16, v144
	v_and_b32_e32 v21, 0xffff0000, v144
	v_pk_mul_f32 v[20:21], v[28:29], v[20:21]
	v_lshlrev_b32_e32 v2, 16, v145
	v_mul_f32_e32 v1, 0x3fb8aa3b, v20
	v_exp_f32_e32 v20, v1
	v_mul_f32_e32 v1, 0x3fb8aa3b, v21
	v_exp_f32_e32 v21, v1
	v_and_b32_e32 v3, 0xffff0000, v145
	v_pk_mul_f32 v[2:3], v[26:27], v[2:3]
	v_xor_b32_e32 v70, 0x80000000, v20
	v_mul_f32_e32 v1, 0x3fb8aa3b, v2
	v_xor_b32_e32 v71, 0x80000000, v21
	v_exp_f32_e32 v2, v1
	v_mul_f32_e32 v1, 0x3fb8aa3b, v3
	v_pk_fma_f32 v[70:71], v[70:71], v[20:21], 1.0 op_sel_hi:[1,1,0]
	v_exp_f32_e32 v3, v1
	v_max_f32_e32 v1, 0, v70
	v_xor_b32_e32 v67, 0x80000000, v3
	v_xor_b32_e32 v66, 0x80000000, v2
	v_pk_fma_f32 v[66:67], v[66:67], v[2:3], 1.0 op_sel_hi:[1,1,0]
	s_waitcnt vmcnt(18)
	v_lshlrev_b32_e32 v62, 16, v148
	v_and_b32_e32 v63, 0xffff0000, v148
	v_lshlrev_b32_e32 v6, 16, v149
	v_and_b32_e32 v7, 0xffff0000, v149
	s_waitcnt vmcnt(17)
	v_lshlrev_b32_e32 v64, 16, v152
	v_and_b32_e32 v65, 0xffff0000, v152
	v_sqrt_f32_e32 v70, v1
	v_max_f32_e32 v1, 0, v71
	v_lshlrev_b32_e32 v36, 16, v153
	v_and_b32_e32 v37, 0xffff0000, v153
	v_sqrt_f32_e32 v71, v1
	v_max_f32_e32 v1, 0, v66
	v_pk_mul_f32 v[62:63], v[70:71], v[62:63]
	v_sqrt_f32_e32 v66, v1
	v_max_f32_e32 v1, 0, v67
	v_sqrt_f32_e32 v67, v1
	s_nop 0
	v_pk_mul_f32 v[6:7], v[66:67], v[6:7]
	s_nop 0
	v_pk_mul_f32 v[6:7], v[6:7], v[36:37]
	v_pk_mul_f32 v[36:37], v[62:63], v[64:65]
	v_pk_fma_f32 v[50:51], v[50:51], v[2:3], v[6:7]
	v_lshlrev_b32_e32 v2, 16, v146
	v_and_b32_e32 v3, 0xffff0000, v146
	v_pk_mul_f32 v[2:3], v[32:33], v[2:3]
	v_lshlrev_b32_e32 v4, 16, v147
	v_mul_f32_e32 v1, 0x3fb8aa3b, v2
	v_exp_f32_e32 v2, v1
	v_mul_f32_e32 v1, 0x3fb8aa3b, v3
	v_exp_f32_e32 v3, v1
	v_and_b32_e32 v5, 0xffff0000, v147
	v_pk_mul_f32 v[4:5], v[30:31], v[4:5]
	v_xor_b32_e32 v62, 0x80000000, v2
	v_mul_f32_e32 v1, 0x3fb8aa3b, v4
	v_xor_b32_e32 v63, 0x80000000, v3
	v_exp_f32_e32 v4, v1
	v_mul_f32_e32 v1, 0x3fb8aa3b, v5
	v_pk_fma_f32 v[62:63], v[62:63], v[2:3], 1.0 op_sel_hi:[1,1,0]
	v_exp_f32_e32 v5, v1
	v_max_f32_e32 v1, 0, v62
	v_pk_fma_f32 v[46:47], v[46:47], v[20:21], v[36:37]
	v_lshlrev_b32_e32 v20, 16, v154
	v_and_b32_e32 v21, 0xffff0000, v154
	v_lshlrev_b32_e32 v36, 16, v155
	v_and_b32_e32 v37, 0xffff0000, v155
	v_xor_b32_e32 v39, 0x80000000, v5
	v_xor_b32_e32 v38, 0x80000000, v4
	v_pk_fma_f32 v[38:39], v[38:39], v[4:5], 1.0 op_sel_hi:[1,1,0]
	v_lshlrev_b32_e32 v6, 16, v150
	v_sqrt_f32_e32 v62, v1
	v_max_f32_e32 v1, 0, v63
	v_and_b32_e32 v7, 0xffff0000, v150
	v_lshlrev_b32_e32 v8, 16, v151
	v_and_b32_e32 v9, 0xffff0000, v151
	v_sqrt_f32_e32 v63, v1
	v_max_f32_e32 v1, 0, v38
	v_pk_mul_f32 v[6:7], v[62:63], v[6:7]
	v_pk_mul_f32 v[6:7], v[6:7], v[20:21]
	v_pk_fma_f32 v[44:45], v[44:45], v[2:3], v[6:7]
	s_waitcnt vmcnt(16)
	v_lshlrev_b32_e32 v2, 16, v156
	v_and_b32_e32 v3, 0xffff0000, v156
	v_pk_mul_f32 v[2:3], v[46:47], v[2:3]
	v_lshlrev_b32_e32 v6, 16, v159
	v_sqrt_f32_e32 v38, v1
	v_max_f32_e32 v1, 0, v39
	v_cvt_pk_bf16_f32 v2, v2, v3
	v_and_b32_e32 v7, 0xffff0000, v159
	v_sqrt_f32_e32 v39, v1
	s_nop 0
	v_pk_mul_f32 v[8:9], v[38:39], v[8:9]
	s_nop 0
	v_pk_mul_f32 v[8:9], v[8:9], v[36:37]
	s_nop 0
	v_pk_fma_f32 v[8:9], v[48:49], v[4:5], v[8:9]
	v_lshlrev_b32_e32 v4, 16, v157
	v_and_b32_e32 v5, 0xffff0000, v157
	v_pk_mul_f32 v[4:5], v[50:51], v[4:5]
	v_pk_mul_f32 v[6:7], v[8:9], v[6:7]
	v_cvt_pk_bf16_f32 v3, v4, v5
	v_lshlrev_b32_e32 v4, 16, v158
	v_and_b32_e32 v5, 0xffff0000, v158
	v_pk_mul_f32 v[4:5], v[44:45], v[4:5]
	s_nop 0
	v_cvt_pk_bf16_f32 v4, v4, v5
	v_cvt_pk_bf16_f32 v5, v6, v7
	global_store_dwordx4 v[224:225], v[2:5], off
	s_nop 0
	s_nop 0
	s_nop 0
	s_waitcnt vmcnt(16)
	v_lshlrev_b32_e32 v2, 16, v160
	v_and_b32_e32 v3, 0xffff0000, v160
	v_pk_mul_f32 v[2:3], v[28:29], v[2:3]
	v_lshlrev_b32_e32 v4, 16, v161
	v_mul_f32_e32 v1, 0x3fb8aa3b, v2
	v_exp_f32_e32 v2, v1
	v_mul_f32_e32 v1, 0x3fb8aa3b, v3
	v_exp_f32_e32 v3, v1
	v_and_b32_e32 v5, 0xffff0000, v161
	v_pk_mul_f32 v[4:5], v[26:27], v[4:5]
	v_xor_b32_e32 v62, 0x80000000, v2
	v_mul_f32_e32 v1, 0x3fb8aa3b, v4
	v_xor_b32_e32 v63, 0x80000000, v3
	v_exp_f32_e32 v4, v1
	v_mul_f32_e32 v1, 0x3fb8aa3b, v5
	v_pk_fma_f32 v[62:63], v[62:63], v[2:3], 1.0 op_sel_hi:[1,1,0]
	v_exp_f32_e32 v5, v1
	v_max_f32_e32 v1, 0, v62
	v_xor_b32_e32 v49, 0x80000000, v5
	v_xor_b32_e32 v48, 0x80000000, v4
	v_pk_fma_f32 v[48:49], v[48:49], v[4:5], 1.0 op_sel_hi:[1,1,0]
	s_waitcnt vmcnt(15)
	v_lshlrev_b32_e32 v40, 16, v164
	v_and_b32_e32 v41, 0xffff0000, v164
	v_lshlrev_b32_e32 v36, 16, v165
	v_and_b32_e32 v37, 0xffff0000, v165
	s_waitcnt vmcnt(14)
; __device__ __forceinline__ f32x4 unpack4(u32x2 u) { return (f32x4){__uint_as_float(u.x << 16), __uint_as_float(u.x & 0xffff0000u), __uint_as_float(u.y << 16), __uint_as_float(u.y & 0xffff0000u)}; }
; __device__ __forceinline__ u32x2 pack4(f32x4 v) { u32x2 r; r.x = cvt_pk_bf16(v.x, v.y); r.y = cvt_pk_bf16(v.z, v.w); return r; }
; template <int ph>
; __device__ __forceinline__ void run_phase(const Args& args, LAS unsigned char* lds, const int G, const int bx, const bool fin = true) {
;     ...
;             auto lru_ab = [](f32x4 gr, f32x4 gi, f32x4 xc, f32x4 sp, f32x4& a, f32x4& bb) {
;                 const f32x4 la = gr * sp; a = (f32x4){__expf(la[0]), __expf(la[1]), __expf(la[2]), __expf(la[3])};
;                 const f32x4 om = (f32x4){1.f, 1.f, 1.f, 1.f} - a * a;
;                 bb = (f32x4){sqrtf(fmaxf(om[0], 0.f)), sqrtf(fmaxf(om[1], 0.f)), sqrtf(fmaxf(om[2], 0.f)), sqrtf(fmaxf(om[3], 0.f))} * gi * xc; };
;     ...
; #pragma unroll 8
;                 for (int t = 0; t < 32; ++t) { const size_t o = base + (size_t)t * D;
;                     const u32x4 gr = *(const u32x4*)(GR + o), gi = *(const u32x4*)(GI + o), xc = *(const u32x4*)(XC + o), gg = *(const u32x4*)(GG + o);
;                     f32x4 a, bb;
;                     lru_ab(unpack4((u32x2){gr.x, gr.y}), unpack4((u32x2){gi.x, gi.y}), unpack4((u32x2){xc.x, xc.y}), sp0, a, bb); h0 = a * h0 + bb;
;                     lru_ab(unpack4((u32x2){gr.z, gr.w}), unpack4((u32x2){gi.z, gi.w}), unpack4((u32x2){xc.z, xc.w}), sp1, a, bb); h1 = a * h1 + bb;
;                     const u32x2 w0 = pack4(h0 * unpack4((u32x2){gg.x, gg.y})), w1 = pack4(h1 * unpack4((u32x2){gg.z, gg.w}));
;                     *(u32x4*)(LO + o) = (u32x4){w0.x, w0.y, w1.x, w1.y}; }
	v_lshlrev_b32_e32 v42, 16, v168
	v_and_b32_e32 v43, 0xffff0000, v168
	v_sqrt_f32_e32 v62, v1
	v_max_f32_e32 v1, 0, v63
	v_lshlrev_b32_e32 v14, 16, v169
	v_and_b32_e32 v15, 0xffff0000, v169
	v_sqrt_f32_e32 v63, v1
	v_max_f32_e32 v1, 0, v48
	v_pk_mul_f32 v[40:41], v[62:63], v[40:41]
	v_sqrt_f32_e32 v48, v1
	v_max_f32_e32 v1, 0, v49
	v_sqrt_f32_e32 v49, v1
	s_nop 0
	v_pk_mul_f32 v[36:37], v[48:49], v[36:37]
	s_nop 0
	v_pk_mul_f32 v[14:15], v[36:37], v[14:15]
	v_pk_mul_f32 v[36:37], v[40:41], v[42:43]
	v_pk_fma_f32 v[4:5], v[50:51], v[4:5], v[14:15]
	v_lshlrev_b32_e32 v14, 16, v162
	v_and_b32_e32 v15, 0xffff0000, v162
	v_pk_mul_f32 v[14:15], v[32:33], v[14:15]
	v_lshlrev_b32_e32 v6, 16, v163
	v_mul_f32_e32 v1, 0x3fb8aa3b, v14
	v_exp_f32_e32 v14, v1
	v_mul_f32_e32 v1, 0x3fb8aa3b, v15
	v_exp_f32_e32 v15, v1
	v_and_b32_e32 v7, 0xffff0000, v163
	v_pk_mul_f32 v[6:7], v[30:31], v[6:7]
	v_pk_fma_f32 v[2:3], v[46:47], v[2:3], v[36:37]
	v_mul_f32_e32 v1, 0x3fb8aa3b, v6
	v_xor_b32_e32 v47, 0x80000000, v15
	v_xor_b32_e32 v46, 0x80000000, v14
	v_exp_f32_e32 v42, v1
	v_mul_f32_e32 v1, 0x3fb8aa3b, v7
	v_pk_fma_f32 v[46:47], v[46:47], v[14:15], 1.0 op_sel_hi:[1,1,0]
	v_exp_f32_e32 v43, v1
	v_max_f32_e32 v1, 0, v46
	v_xor_b32_e32 v7, 0x80000000, v43
	v_xor_b32_e32 v6, 0x80000000, v42
	v_pk_fma_f32 v[6:7], v[6:7], v[42:43], 1.0 op_sel_hi:[1,1,0]
	v_lshlrev_b32_e32 v36, 16, v166
	v_and_b32_e32 v37, 0xffff0000, v166
	v_lshlrev_b32_e32 v38, 16, v167
	v_and_b32_e32 v39, 0xffff0000, v167
	v_lshlrev_b32_e32 v40, 16, v170
	v_and_b32_e32 v41, 0xffff0000, v170
	v_sqrt_f32_e32 v46, v1
	v_max_f32_e32 v1, 0, v47
	v_lshlrev_b32_e32 v16, 16, v171
	v_and_b32_e32 v17, 0xffff0000, v171
	v_sqrt_f32_e32 v47, v1
	v_max_f32_e32 v1, 0, v6
	v_pk_mul_f32 v[36:37], v[46:47], v[36:37]
	v_sqrt_f32_e32 v6, v1
	v_max_f32_e32 v1, 0, v7
	v_sqrt_f32_e32 v7, v1
	s_nop 0
	v_pk_mul_f32 v[6:7], v[6:7], v[38:39]
	s_nop 0
	v_pk_mul_f32 v[16:17], v[6:7], v[16:17]
	v_pk_mul_f32 v[6:7], v[36:37], v[40:41]
	v_pk_fma_f32 v[8:9], v[8:9], v[42:43], v[16:17]
	v_pk_fma_f32 v[6:7], v[44:45], v[14:15], v[6:7]
	s_waitcnt vmcnt(13)
	v_lshlrev_b32_e32 v14, 16, v172
	v_and_b32_e32 v15, 0xffff0000, v172
	v_lshlrev_b32_e32 v16, 16, v173
	v_and_b32_e32 v17, 0xffff0000, v173
	v_pk_mul_f32 v[16:17], v[4:5], v[16:17]
	v_pk_mul_f32 v[14:15], v[2:3], v[14:15]
	v_lshlrev_b32_e32 v18, 16, v175
	v_cvt_pk_bf16_f32 v14, v14, v15
	v_cvt_pk_bf16_f32 v15, v16, v17
	v_lshlrev_b32_e32 v16, 16, v174
	v_and_b32_e32 v17, 0xffff0000, v174
	v_and_b32_e32 v19, 0xffff0000, v175
	v_pk_mul_f32 v[18:19], v[8:9], v[18:19]
	v_pk_mul_f32 v[16:17], v[6:7], v[16:17]
	s_nop 0
	v_cvt_pk_bf16_f32 v16, v16, v17
	v_cvt_pk_bf16_f32 v17, v18, v19
	global_store_dwordx4 v[224:225], v[14:17], off offset:2048
	s_nop 1
	s_nop 1
	s_nop 0
	s_waitcnt vmcnt(12)
	v_lshlrev_b32_e32 v40, 16, v180
	v_lshlrev_b32_e32 v38, 16, v176
	v_and_b32_e32 v39, 0xffff0000, v176
	v_pk_mul_f32 v[38:39], v[28:29], v[38:39]
	v_lshlrev_b32_e32 v14, 16, v177
	v_mul_f32_e32 v1, 0x3fb8aa3b, v38
	v_exp_f32_e32 v38, v1
	v_mul_f32_e32 v1, 0x3fb8aa3b, v39
	v_exp_f32_e32 v39, v1
	v_and_b32_e32 v15, 0xffff0000, v177
	v_pk_mul_f32 v[14:15], v[26:27], v[14:15]
	v_xor_b32_e32 v66, 0x80000000, v38
	v_mul_f32_e32 v1, 0x3fb8aa3b, v14
	v_xor_b32_e32 v67, 0x80000000, v39
	v_exp_f32_e32 v14, v1
	v_mul_f32_e32 v1, 0x3fb8aa3b, v15
	v_pk_fma_f32 v[66:67], v[66:67], v[38:39], 1.0 op_sel_hi:[1,1,0]
	v_exp_f32_e32 v15, v1
	v_max_f32_e32 v1, 0, v66
	v_xor_b32_e32 v65, 0x80000000, v15
	v_xor_b32_e32 v64, 0x80000000, v14
	v_pk_fma_f32 v[64:65], v[64:65], v[14:15], 1.0 op_sel_hi:[1,1,0]
	v_and_b32_e32 v41, 0xffff0000, v180
	v_lshlrev_b32_e32 v18, 16, v181
	v_and_b32_e32 v19, 0xffff0000, v181
	s_waitcnt vmcnt(11)
	v_lshlrev_b32_e32 v62, 16, v184
	v_and_b32_e32 v63, 0xffff0000, v184
	v_lshlrev_b32_e32 v44, 16, v185
	v_sqrt_f32_e32 v66, v1
	v_max_f32_e32 v1, 0, v67
	v_and_b32_e32 v45, 0xffff0000, v185
	v_sqrt_f32_e32 v67, v1
	v_max_f32_e32 v1, 0, v64
	v_pk_mul_f32 v[40:41], v[66:67], v[40:41]
	v_pk_mul_f32 v[40:41], v[40:41], v[62:63]
	v_pk_fma_f32 v[2:3], v[2:3], v[38:39], v[40:41]
	v_lshlrev_b32_e32 v38, 16, v187
	v_and_b32_e32 v39, 0xffff0000, v187
	v_sqrt_f32_e32 v64, v1
	v_max_f32_e32 v1, 0, v65
	v_sqrt_f32_e32 v65, v1
	s_nop 0
	v_pk_mul_f32 v[18:19], v[64:65], v[18:19]
	s_nop 0
	v_pk_mul_f32 v[18:19], v[18:19], v[44:45]
	s_nop 0
	v_pk_fma_f32 v[40:41], v[4:5], v[14:15], v[18:19]
	v_lshlrev_b32_e32 v4, 16, v178
	v_and_b32_e32 v5, 0xffff0000, v178
	v_pk_mul_f32 v[4:5], v[32:33], v[4:5]
	v_lshlrev_b32_e32 v14, 16, v179
	v_mul_f32_e32 v1, 0x3fb8aa3b, v4
	v_exp_f32_e32 v4, v1
	v_mul_f32_e32 v1, 0x3fb8aa3b, v5
	v_exp_f32_e32 v5, v1
	v_and_b32_e32 v15, 0xffff0000, v179
	v_pk_mul_f32 v[14:15], v[30:31], v[14:15]
	v_lshlrev_b32_e32 v16, 16, v182
	v_and_b32_e32 v17, 0xffff0000, v182
	v_lshlrev_b32_e32 v18, 16, v183
	v_and_b32_e32 v19, 0xffff0000, v183
	v_lshlrev_b32_e32 v20, 16, v186
	v_and_b32_e32 v21, 0xffff0000, v186
	v_mul_f32_e32 v1, 0x3fb8aa3b, v14
	v_xor_b32_e32 v47, 0x80000000, v5
	v_xor_b32_e32 v46, 0x80000000, v4
	v_exp_f32_e32 v14, v1
	v_mul_f32_e32 v1, 0x3fb8aa3b, v15
	v_pk_fma_f32 v[46:47], v[46:47], v[4:5], 1.0 op_sel_hi:[1,1,0]
	v_exp_f32_e32 v15, v1
	v_max_f32_e32 v1, 0, v46
	v_xor_b32_e32 v45, 0x80000000, v15
	v_xor_b32_e32 v44, 0x80000000, v14
	v_pk_fma_f32 v[44:45], v[44:45], v[14:15], 1.0 op_sel_hi:[1,1,0]
	v_sqrt_f32_e32 v46, v1
	v_max_f32_e32 v1, 0, v47
	v_sqrt_f32_e32 v47, v1
	v_max_f32_e32 v1, 0, v44
	v_pk_mul_f32 v[16:17], v[46:47], v[16:17]
	v_pk_mul_f32 v[16:17], v[16:17], v[20:21]
	v_sqrt_f32_e32 v44, v1
	v_max_f32_e32 v1, 0, v45
	v_sqrt_f32_e32 v45, v1
	s_nop 0
	v_pk_mul_f32 v[18:19], v[44:45], v[18:19]
	s_nop 0
	v_pk_mul_f32 v[18:19], v[18:19], v[38:39]
	v_pk_fma_f32 v[38:39], v[6:7], v[4:5], v[16:17]
	s_waitcnt vmcnt(10)
; __device__ __forceinline__ f32x4 unpack4(u32x2 u) { return (f32x4){__uint_as_float(u.x << 16), __uint_as_float(u.x & 0xffff0000u), __uint_as_float(u.y << 16), __uint_as_float(u.y & 0xffff0000u)}; }
; __device__ __forceinline__ u32x2 pack4(f32x4 v) { u32x2 r; r.x = cvt_pk_bf16(v.x, v.y); r.y = cvt_pk_bf16(v.z, v.w); return r; }
; template <int ph>
; __device__ __forceinline__ void run_phase(const Args& args, LAS unsigned char* lds, const int G, const int bx, const bool fin = true) {
;     ...
;             auto lru_ab = [](f32x4 gr, f32x4 gi, f32x4 xc, f32x4 sp, f32x4& a, f32x4& bb) {
;                 const f32x4 la = gr * sp; a = (f32x4){__expf(la[0]), __expf(la[1]), __expf(la[2]), __expf(la[3])};
;                 const f32x4 om = (f32x4){1.f, 1.f, 1.f, 1.f} - a * a;
;                 bb = (f32x4){sqrtf(fmaxf(om[0], 0.f)), sqrtf(fmaxf(om[1], 0.f)), sqrtf(fmaxf(om[2], 0.f)), sqrtf(fmaxf(om[3], 0.f))} * gi * xc; };
;     ...
; #pragma unroll 8
;                 for (int t = 0; t < 32; ++t) { const size_t o = base + (size_t)t * D;
;                     const u32x4 gr = *(const u32x4*)(GR + o), gi = *(const u32x4*)(GI + o), xc = *(const u32x4*)(XC + o), gg = *(const u32x4*)(GG + o);
;                     f32x4 a, bb;
;                     lru_ab(unpack4((u32x2){gr.x, gr.y}), unpack4((u32x2){gi.x, gi.y}), unpack4((u32x2){xc.x, xc.y}), sp0, a, bb); h0 = a * h0 + bb;
;                     lru_ab(unpack4((u32x2){gr.z, gr.w}), unpack4((u32x2){gi.z, gi.w}), unpack4((u32x2){xc.z, xc.w}), sp1, a, bb); h1 = a * h1 + bb;
;                     const u32x2 w0 = pack4(h0 * unpack4((u32x2){gg.x, gg.y})), w1 = pack4(h1 * unpack4((u32x2){gg.z, gg.w}));
;                     *(u32x4*)(LO + o) = (u32x4){w0.x, w0.y, w1.x, w1.y}; }
;                 if (seg == 63) { *(f32x4*)(out + O_PLRU + (size_t)b * D + ch) = h0; *(f32x4*)(out + O_PLRU + (size_t)b * D + ch + 4) = h1; }
	v_lshlrev_b32_e32 v4, 16, v188
	v_and_b32_e32 v5, 0xffff0000, v188
	v_lshlrev_b32_e32 v6, 16, v189
	v_and_b32_e32 v7, 0xffff0000, v189
	v_pk_mul_f32 v[6:7], v[40:41], v[6:7]
	v_pk_mul_f32 v[4:5], v[2:3], v[4:5]
	v_pk_fma_f32 v[8:9], v[8:9], v[14:15], v[18:19]
	v_cvt_pk_bf16_f32 v4, v4, v5
	v_cvt_pk_bf16_f32 v5, v6, v7
	v_lshlrev_b32_e32 v6, 16, v190
	v_and_b32_e32 v7, 0xffff0000, v190
	v_lshlrev_b32_e32 v14, 16, v191
	v_and_b32_e32 v15, 0xffff0000, v191
	v_pk_mul_f32 v[14:15], v[8:9], v[14:15]
	v_pk_mul_f32 v[6:7], v[38:39], v[6:7]
	s_nop 0
	v_cvt_pk_bf16_f32 v6, v6, v7
	v_cvt_pk_bf16_f32 v7, v14, v15
	global_store_dwordx4 v[238:239], v[4:7], off
	s_nop 0
	s_nop 0
	s_waitcnt vmcnt(10)
	v_lshlrev_b32_e32 v42, 16, v192
	v_and_b32_e32 v43, 0xffff0000, v192
	v_pk_mul_f32 v[42:43], v[28:29], v[42:43]
	v_lshlrev_b32_e32 v18, 16, v193
	v_mul_f32_e32 v1, 0x3fb8aa3b, v42
	v_exp_f32_e32 v42, v1
	v_mul_f32_e32 v1, 0x3fb8aa3b, v43
	v_exp_f32_e32 v43, v1
	v_and_b32_e32 v19, 0xffff0000, v193
	v_pk_mul_f32 v[18:19], v[26:27], v[18:19]
	v_xor_b32_e32 v50, 0x80000000, v42
	v_mul_f32_e32 v1, 0x3fb8aa3b, v18
	v_xor_b32_e32 v51, 0x80000000, v43
	v_exp_f32_e32 v18, v1
	v_mul_f32_e32 v1, 0x3fb8aa3b, v19
	v_pk_fma_f32 v[50:51], v[50:51], v[42:43], 1.0 op_sel_hi:[1,1,0]
	v_exp_f32_e32 v19, v1
	v_max_f32_e32 v1, 0, v50
	v_xor_b32_e32 v49, 0x80000000, v19
	v_xor_b32_e32 v48, 0x80000000, v18
	v_pk_fma_f32 v[48:49], v[48:49], v[18:19], 1.0 op_sel_hi:[1,1,0]
	s_waitcnt vmcnt(9)
	v_lshlrev_b32_e32 v44, 16, v196
	v_and_b32_e32 v45, 0xffff0000, v196
	v_lshlrev_b32_e32 v14, 16, v197
	v_and_b32_e32 v15, 0xffff0000, v197
	s_waitcnt vmcnt(8)
	v_lshlrev_b32_e32 v46, 16, v204
	v_and_b32_e32 v47, 0xffff0000, v204
	v_sqrt_f32_e32 v50, v1
	v_max_f32_e32 v1, 0, v51
	v_lshlrev_b32_e32 v4, 16, v205
	v_and_b32_e32 v5, 0xffff0000, v205
	v_sqrt_f32_e32 v51, v1
	v_max_f32_e32 v1, 0, v48
	v_pk_mul_f32 v[44:45], v[50:51], v[44:45]
	v_pk_mul_f32 v[44:45], v[44:45], v[46:47]
	v_pk_fma_f32 v[2:3], v[2:3], v[42:43], v[44:45]
	v_sqrt_f32_e32 v48, v1
	v_max_f32_e32 v1, 0, v49
	v_sqrt_f32_e32 v49, v1
	s_nop 0
	v_pk_mul_f32 v[14:15], v[48:49], v[14:15]
	s_nop 0
	v_pk_mul_f32 v[4:5], v[14:15], v[4:5]
	v_lshlrev_b32_e32 v14, 16, v194
	v_and_b32_e32 v15, 0xffff0000, v194
	v_pk_mul_f32 v[14:15], v[32:33], v[14:15]
	v_pk_fma_f32 v[4:5], v[40:41], v[18:19], v[4:5]
	v_mul_f32_e32 v1, 0x3fb8aa3b, v14
	v_exp_f32_e32 v14, v1
	v_mul_f32_e32 v1, 0x3fb8aa3b, v15
	v_exp_f32_e32 v15, v1
	v_lshlrev_b32_e32 v18, 16, v195
	v_and_b32_e32 v19, 0xffff0000, v195
	v_pk_mul_f32 v[18:19], v[30:31], v[18:19]
	v_xor_b32_e32 v45, 0x80000000, v15
	v_mul_f32_e32 v1, 0x3fb8aa3b, v18
	v_xor_b32_e32 v44, 0x80000000, v14
	v_exp_f32_e32 v18, v1
	v_mul_f32_e32 v1, 0x3fb8aa3b, v19
	v_pk_fma_f32 v[44:45], v[44:45], v[14:15], 1.0 op_sel_hi:[1,1,0]
	v_exp_f32_e32 v19, v1
	v_max_f32_e32 v1, 0, v44
	v_xor_b32_e32 v43, 0x80000000, v19
	v_xor_b32_e32 v42, 0x80000000, v18
	v_pk_fma_f32 v[42:43], v[42:43], v[18:19], 1.0 op_sel_hi:[1,1,0]
	v_lshlrev_b32_e32 v20, 16, v198
	v_and_b32_e32 v21, 0xffff0000, v198
	v_lshlrev_b32_e32 v16, 16, v199
	v_and_b32_e32 v17, 0xffff0000, v199
	v_lshlrev_b32_e32 v40, 16, v206
	v_and_b32_e32 v41, 0xffff0000, v206
	v_sqrt_f32_e32 v44, v1
	v_max_f32_e32 v1, 0, v45
	v_lshlrev_b32_e32 v6, 16, v207
	v_and_b32_e32 v7, 0xffff0000, v207
	v_sqrt_f32_e32 v45, v1
	v_max_f32_e32 v1, 0, v42
	v_pk_mul_f32 v[20:21], v[44:45], v[20:21]
	v_pk_mul_f32 v[20:21], v[20:21], v[40:41]
	v_sqrt_f32_e32 v42, v1
	v_max_f32_e32 v1, 0, v43
	v_sqrt_f32_e32 v43, v1
	s_nop 0
	v_pk_mul_f32 v[16:17], v[42:43], v[16:17]
	s_nop 0
	v_pk_mul_f32 v[6:7], v[16:17], v[6:7]
	s_nop 0
	v_pk_fma_f32 v[8:9], v[8:9], v[18:19], v[6:7]
	v_pk_fma_f32 v[6:7], v[38:39], v[14:15], v[20:21]
	s_waitcnt vmcnt(7)
	v_lshlrev_b32_e32 v14, 16, v208
	v_and_b32_e32 v15, 0xffff0000, v208
	v_lshlrev_b32_e32 v10, 16, v209
	v_and_b32_e32 v11, 0xffff0000, v209
	v_pk_mul_f32 v[16:17], v[4:5], v[10:11]
	v_pk_mul_f32 v[10:11], v[2:3], v[14:15]
	v_lshlrev_b32_e32 v14, 16, v210
	v_and_b32_e32 v15, 0xffff0000, v210
	v_lshlrev_b32_e32 v12, 16, v211
	v_and_b32_e32 v13, 0xffff0000, v211
	v_cvt_pk_bf16_f32 v10, v10, v11
	v_cvt_pk_bf16_f32 v11, v16, v17
	v_pk_mul_f32 v[16:17], v[8:9], v[12:13]
	v_pk_mul_f32 v[12:13], v[6:7], v[14:15]
	s_nop 0
	v_cvt_pk_bf16_f32 v12, v12, v13
	v_cvt_pk_bf16_f32 v13, v16, v17
	global_store_dwordx4 v[238:239], v[10:13], off offset:2048
	s_cbranch_scc0 .LBB0_1073
	s_and_saveexec_b64 s[0:1], s[4:5]
	s_cbranch_execz .LBB0_1043
	s_lshl_b64 s[10:11], s[22:23], 12
	s_add_u32 s10, s59, s10
	s_addc_u32 s11, s60, s11
	global_store_dwordx4 v60, v[2:5], s[10:11]
	global_store_dwordx4 v60, v[6:9], s[10:11] offset:16
	s_branch .LBB0_1043
